# up-projection epilogue: dropped zero-initialisation of DPP row-rotate destinations (every lane is written) and the sequence-start zeroing selects in the 16-row groups that can never reach it
# speedup vs baseline: 1.0064x; 1.0064x over previous
; #define PG8_LAS __attribute__((address_space(3)))
; __device__ __forceinline__ float dpp_ror1(float v) { return __int_as_float(__builtin_amdgcn_update_dpp(0, __float_as_int(v), 0x121, 0xf, 0xf, false)); }
; __device__ __forceinline__ float dpp_ror2(float v) { return __int_as_float(__builtin_amdgcn_update_dpp(0, __float_as_int(v), 0x122, 0xf, 0xf, false)); }
;     __device__ __forceinline__ void operator()(const f32x4 (&acc)[2][2][4][2], const Unit& u, int wr, int wc, int fr, int fq) const {
;     ...
;         asm volatile("s_waitcnt lgkmcnt(0)" ::: "memory"); __builtin_amdgcn_s_barrier(); asm volatile("" ::: "memory");
;         f32x4 w0[2], w1[2], w2[2], bb[2];
; #pragma unroll
;         for (int n = 0; n < 2; ++n) { w0[n] = *(const f32x4*)(cw + f0 + 4 * n); w1[n] = *(const f32x4*)(cw + 2816 + f0 + 4 * n); w2[n] = *(const f32x4*)(cw + 2 * 2816 + f0 + 4 * n); bb[n] = *(const f32x4*)(cb + f0 + 4 * n); }
; #pragma unroll
;         for (int ai = 0; ai < 2; ++ai) {
;             const int blk = ai * 2 + wr;
;             f32x4 pc1[2], pc2[2];
; #pragma unroll
;             for (int n = 0; n < 2; ++n) { f32x4 hv = {0.f, 0.f, 0.f, 0.f};
;                 if (blk > 0 && fr >= 14) hv = *(const PG8_LAS f32x4*)(halo + ((blk - 1) * 2 + (fr - 14)) * 128 + fl + 4 * n);
; #pragma unroll
;                 for (int j = 0; j < 4; ++j) { pc1[n][j] = dpp_ror1(hv[j]); pc2[n][j] = dpp_ror2(hv[j]); } }
; #pragma unroll
;             for (int m = 0; m < 4; ++m) { const int r = ai * HALF + wr * 64 + m * 16 + fr, tk = 254 * i - 2 + r;
;                 f32x4 o[2];
; #pragma unroll
;                 for (int n = 0; n < 2; ++n) { f32x4 cur = acc[ai][0][m][n] * rn[ai][m]; if (tk < 0) cur = (f32x4){0.f, 0.f, 0.f, 0.f};
; #pragma unroll
;                     for (int j = 0; j < 4; ++j) { const float c1 = dpp_ror1(cur[j]), c2 = dpp_ror2(cur[j]);
;                         const float p1 = fr >= 1 ? c1 : pc1[n][j], p2 = fr >= 2 ? c2 : pc2[n][j]; pc1[n][j] = c1; pc2[n][j] = c2;
.LBB0_293:
	s_or_b64 exec, exec, s[6:7]
	v_lshl_or_b32 v182, s8, 7, v173
	v_ashrrev_i32_e32 v183, 31, v182
	v_lshlrev_b64 v[64:65], 2, v[182:183]
	s_waitcnt lgkmcnt(0)
	s_barrier
	v_lshl_add_u64 v[66:67], s[20:21], 0, v[64:65]
	v_lshl_add_u64 v[68:69], s[66:67], 0, v[64:65]
	v_lshl_add_u64 v[76:77], s[68:69], 0, v[64:65]
	v_lshl_add_u64 v[100:101], s[26:27], 0, v[64:65]
	global_load_dwordx4 v[72:75], v[66:67], off offset:16
	global_load_dwordx4 v[96:99], v[66:67], off
	s_nop 0
	global_load_dwordx4 v[64:67], v[68:69], off offset:16
	global_load_dwordx4 v[88:91], v[68:69], off
	s_nop 0
	global_load_dwordx4 v[68:71], v[76:77], off offset:16
	global_load_dwordx4 v[92:95], v[76:77], off
	s_nop 0
	global_load_dwordx4 v[76:79], v[100:101], off offset:16
	s_nop 0
	global_load_dwordx4 v[100:103], v[100:101], off
	v_mov_b32_e32 v160, 0
	v_mov_b32_e32 v162, 0
	v_mov_b32_e32 v163, 0
	v_mov_b32_e32 v164, 0
	v_mov_b32_e32 v165, 0
	s_and_saveexec_b64 s[6:7], s[60:61]
	ds_read_b128 v[162:165], v206
	s_or_b64 exec, exec, s[6:7]
	s_waitcnt lgkmcnt(0)
	v_mov_b32_dpp v228, v162 row_ror:1 row_mask:0xf bank_mask:0xf
	v_mov_b32_dpp v230, v162 row_ror:2 row_mask:0xf bank_mask:0xf
	v_mov_b32_dpp v229, v163 row_ror:1 row_mask:0xf bank_mask:0xf
	v_mov_b32_dpp v231, v163 row_ror:2 row_mask:0xf bank_mask:0xf
	v_mov_b32_dpp v236, v164 row_ror:1 row_mask:0xf bank_mask:0xf
	v_mov_b32_dpp v238, v164 row_ror:2 row_mask:0xf bank_mask:0xf
	v_mov_b32_dpp v237, v165 row_ror:1 row_mask:0xf bank_mask:0xf
	v_mov_b32_dpp v239, v165 row_ror:2 row_mask:0xf bank_mask:0xf
	v_mov_b32_e32 v161, 0
	v_mov_b32_e32 v162, 0
	v_mov_b32_e32 v163, 0
	s_and_saveexec_b64 s[6:7], s[60:61]
	ds_read_b128 v[160:163], v206 offset:16
	s_or_b64 exec, exec, s[6:7]
	v_pk_add_f32 v[164:165], v[192:193], v[194:195]
	s_add_i32 s77, s77, -2
	v_pk_fma_f32 v[164:165], v[164:165], s[78:79], v[210:211] op_sel_hi:[1,0,0]
	v_add_u32_e32 v227, s77, v172
	v_mul_f32_e32 v192, 0x4b800000, v165
	v_cmp_gt_f32_e64 s[8:9], s39, v165
	s_nop 1
	v_cndmask_b32_e64 v165, v165, v192, s[8:9]
	v_rsq_f32_e32 v165, v165
	s_waitcnt lgkmcnt(0)
	v_mov_b32_dpp v240, v160 row_ror:1 row_mask:0xf bank_mask:0xf
	v_mul_f32_e32 v192, 0x45800000, v165
	v_cndmask_b32_e64 v192, v165, v192, s[8:9]
	v_pk_mul_f32 v[156:157], v[156:157], v[192:193] op_sel_hi:[1,0]
	v_cmp_gt_i32_e64 s[8:9], 0, v227
	v_pk_mul_f32 v[158:159], v[158:159], v[192:193] op_sel_hi:[1,0]
	s_nop 0
	v_cndmask_b32_e64 v157, v157, 0, s[8:9]
	v_mov_b32_dpp v242, v160 row_ror:2 row_mask:0xf bank_mask:0xf
	v_mov_b32_dpp v241, v161 row_ror:1 row_mask:0xf bank_mask:0xf
	v_mov_b32_dpp v193, v157 row_ror:1 row_mask:0xf bank_mask:0xf
	v_mov_b32_dpp v243, v161 row_ror:2 row_mask:0xf bank_mask:0xf
	v_pk_mul_f32 v[160:161], v[152:153], v[192:193] op_sel_hi:[1,0]
	v_pk_mul_f32 v[152:153], v[154:155], v[192:193] op_sel_hi:[1,0]
	v_mov_b32_dpp v232, v162 row_ror:1 row_mask:0xf bank_mask:0xf
	v_mov_b32_dpp v234, v162 row_ror:2 row_mask:0xf bank_mask:0xf
	v_mov_b32_dpp v233, v163 row_ror:1 row_mask:0xf bank_mask:0xf
	v_mov_b32_dpp v235, v163 row_ror:2 row_mask:0xf bank_mask:0xf
	v_cndmask_b32_e64 v159, v159, 0, s[8:9]
	v_cndmask_b32_e64 v158, v158, 0, s[8:9]
	v_cndmask_b32_e64 v156, v156, 0, s[8:9]
	v_cndmask_b32_e64 v153, v153, 0, s[8:9]
	v_cndmask_b32_e64 v152, v152, 0, s[8:9]
	v_cndmask_b32_e64 v155, v161, 0, s[8:9]
	v_cndmask_b32_e64 v154, v160, 0, s[8:9]
	v_cmp_gt_i32_e64 s[8:9], s83, v227
	s_lshl_b32 s71, s76, 12
	v_cmp_gt_f32_e64 s[6:7], s39, v164
	v_mov_b32_dpp v165, v156 row_ror:1 row_mask:0xf bank_mask:0xf
	v_mov_b32_dpp v194, v156 row_ror:2 row_mask:0xf bank_mask:0xf
	v_mov_b32_dpp v195, v157 row_ror:2 row_mask:0xf bank_mask:0xf
	v_mov_b32_dpp v219, v158 row_ror:1 row_mask:0xf bank_mask:0xf
	v_mov_b32_dpp v221, v158 row_ror:2 row_mask:0xf bank_mask:0xf
	v_mov_b32_dpp v220, v159 row_ror:1 row_mask:0xf bank_mask:0xf
	v_mov_b32_dpp v222, v159 row_ror:2 row_mask:0xf bank_mask:0xf
	v_mov_b32_dpp v223, v154 row_ror:1 row_mask:0xf bank_mask:0xf
	v_mov_b32_dpp v225, v154 row_ror:2 row_mask:0xf bank_mask:0xf
	v_mov_b32_dpp v224, v155 row_ror:1 row_mask:0xf bank_mask:0xf
	v_mov_b32_dpp v226, v155 row_ror:2 row_mask:0xf bank_mask:0xf
	v_mov_b32_dpp v160, v152 row_ror:1 row_mask:0xf bank_mask:0xf
	v_mov_b32_dpp v162, v152 row_ror:2 row_mask:0xf bank_mask:0xf
	v_mov_b32_dpp v161, v153 row_ror:1 row_mask:0xf bank_mask:0xf
	v_mov_b32_dpp v163, v153 row_ror:2 row_mask:0xf bank_mask:0xf
	s_and_b64 s[18:19], s[46:47], s[8:9]
	s_waitcnt vmcnt(0)
	s_and_saveexec_b64 s[8:9], s[18:19]
	s_cbranch_execz .LBB0_299
; __device__ __forceinline__ u32x4 pack8(const f32x4& v0, const f32x4& v1) { u32x4 w; w.x = cvt_pk_bf16(v0[0], v0[1]); w.y = cvt_pk_bf16(v0[2], v0[3]); w.z = cvt_pk_bf16(v1[0], v1[1]); w.w = cvt_pk_bf16(v1[2], v1[3]); return w; }
; __device__ __forceinline__ float dpp_ror1(float v) { return __int_as_float(__builtin_amdgcn_update_dpp(0, __float_as_int(v), 0x121, 0xf, 0xf, false)); }
; __device__ __forceinline__ float dpp_ror2(float v) { return __int_as_float(__builtin_amdgcn_update_dpp(0, __float_as_int(v), 0x122, 0xf, 0xf, false)); }
;     __device__ __forceinline__ void operator()(const f32x4 (&acc)[2][2][4][2], const Unit& u, int wr, int wc, int fr, int fq) const {
;     ...
;                     for (int j = 0; j < 4; ++j) { const float c1 = dpp_ror1(cur[j]), c2 = dpp_ror2(cur[j]);
;                         const float p1 = fr >= 1 ? c1 : pc1[n][j], p2 = fr >= 2 ? c2 : pc2[n][j]; pc1[n][j] = c1; pc2[n][j] = c2;
;                         const float cv = bb[n][j] + w0[n][j] * p2 + w1[n][j] * p1 + w2[n][j] * cur[j];
;                         o[n][j] = gelu_t(cv) * (acc[ai][1][m][n][j] * rn[ai][m]); } }
;                 if (r >= 2 && tk < 4096) *(u32x4*)(ACT + (size_t)(b * 4096 + tk) * 2816 + f0) = pack8(o[0], o[1]); }
	v_cndmask_b32_e64 v213, v243, v226, s[44:45]
	v_cndmask_b32_e64 v212, v242, v225, s[44:45]
	v_pk_fma_f32 v[212:213], v[72:73], v[212:213], v[76:77]
	v_cndmask_b32_e64 v215, v224, v241, s[42:43]
	v_cndmask_b32_e64 v214, v223, v240, s[42:43]
	v_pk_fma_f32 v[212:213], v[64:65], v[214:215], v[212:213]
	v_pk_mul_f32 v[144:145], v[144:145], v[192:193] op_sel_hi:[1,0]
	v_pk_fma_f32 v[154:155], v[154:155], v[68:69], v[212:213]
	v_pk_mul_f32 v[150:151], v[150:151], v[192:193] op_sel_hi:[1,0]
	v_mul_f32_e32 v212, 0x3d122279, v154
	v_mul_f32_e32 v213, 0x3d122279, v155
	v_fmaak_f32 v212, v154, v212, 0x3f4c422a
	v_fmaak_f32 v213, v155, v213, 0x3f4c422a
	v_mul_f32_e32 v212, v154, v212
	v_mul_f32_e32 v213, v155, v213
	v_mul_f32_e32 v212, 0xc038aa3b, v212
	v_mul_f32_e32 v213, 0xc038aa3b, v213
	v_exp_f32_e32 v212, v212
	v_exp_f32_e32 v213, v213
	v_pk_mul_f32 v[148:149], v[148:149], v[192:193] op_sel_hi:[1,0]
	v_pk_mul_f32 v[146:147], v[146:147], v[192:193] op_sel_hi:[1,0]
	v_add_f32_e32 v212, 1.0, v212
	v_add_f32_e32 v213, 1.0, v213
	v_rcp_f32_e32 v212, v212
	v_rcp_f32_e32 v213, v213
	s_nop 0
	v_pk_mul_f32 v[154:155], v[154:155], v[212:213]
	s_nop 0
	v_pk_mul_f32 v[154:155], v[144:145], v[154:155]
	v_cndmask_b32_e64 v145, v239, v222, s[44:45]
	v_cndmask_b32_e64 v144, v238, v221, s[44:45]
	v_pk_fma_f32 v[144:145], v[98:99], v[144:145], v[102:103]
	v_cndmask_b32_e64 v213, v220, v237, s[42:43]
	v_cndmask_b32_e64 v212, v219, v236, s[42:43]
	v_pk_fma_f32 v[144:145], v[90:91], v[212:213], v[144:145]
	s_nop 0
	v_pk_fma_f32 v[144:145], v[158:159], v[94:95], v[144:145]
	s_nop 0
	v_mul_f32_e32 v158, 0x3d122279, v144
	v_mul_f32_e32 v159, 0x3d122279, v145
	v_fmaak_f32 v158, v144, v158, 0x3f4c422a
	v_fmaak_f32 v159, v145, v159, 0x3f4c422a
	v_mul_f32_e32 v158, v144, v158
	v_mul_f32_e32 v159, v145, v159
	v_mul_f32_e32 v158, 0xc038aa3b, v158
	v_mul_f32_e32 v159, 0xc038aa3b, v159
	v_exp_f32_e32 v158, v158
	v_exp_f32_e32 v159, v159
	v_add_f32_e32 v158, 1.0, v158
	v_add_f32_e32 v159, 1.0, v159
	v_rcp_f32_e32 v158, v158
	v_rcp_f32_e32 v159, v159
	s_nop 0
	v_pk_mul_f32 v[144:145], v[144:145], v[158:159]
	s_nop 0
	v_pk_mul_f32 v[150:151], v[150:151], v[144:145]
	v_cndmask_b32_e64 v145, v231, v195, s[44:45]
	v_cndmask_b32_e64 v144, v230, v194, s[44:45]
	v_pk_fma_f32 v[144:145], v[96:97], v[144:145], v[100:101]
	v_cndmask_b32_e64 v159, v193, v229, s[42:43]
	v_cndmask_b32_e64 v158, v165, v228, s[42:43]
	v_pk_fma_f32 v[144:145], v[88:89], v[158:159], v[144:145]
	s_nop 0
	v_pk_fma_f32 v[144:145], v[156:157], v[92:93], v[144:145]
	s_nop 0
	v_mul_f32_e32 v156, 0x3d122279, v144
	v_mul_f32_e32 v157, 0x3d122279, v145
	v_fmaak_f32 v156, v144, v156, 0x3f4c422a
	v_fmaak_f32 v157, v145, v157, 0x3f4c422a
	v_mul_f32_e32 v156, v144, v156
	v_mul_f32_e32 v157, v145, v157
	v_mul_f32_e32 v156, 0xc038aa3b, v156
	v_mul_f32_e32 v157, 0xc038aa3b, v157
	v_exp_f32_e32 v156, v156
	v_exp_f32_e32 v157, v157
	v_add_f32_e32 v156, 1.0, v156
	v_add_f32_e32 v157, 1.0, v157
	v_rcp_f32_e32 v156, v156
	v_rcp_f32_e32 v157, v157
	s_nop 0
	v_pk_mul_f32 v[144:145], v[144:145], v[156:157]
	s_nop 0
	v_pk_mul_f32 v[144:145], v[148:149], v[144:145]
	v_cndmask_b32_e64 v149, v235, v163, s[44:45]
	v_cndmask_b32_e64 v148, v234, v162, s[44:45]
	v_cndmask_b32_e64 v157, v161, v233, s[42:43]
	v_cndmask_b32_e64 v156, v160, v232, s[42:43]
	v_pk_fma_f32 v[148:149], v[74:75], v[148:149], v[78:79]
	v_cvt_pk_bf16_f32 v144, v144, v145
	v_pk_fma_f32 v[148:149], v[66:67], v[156:157], v[148:149]
	v_cvt_pk_bf16_f32 v145, v150, v151
	v_pk_fma_f32 v[148:149], v[152:153], v[70:71], v[148:149]
	v_add_u32_e32 v150, s71, v227
	v_mul_f32_e32 v152, 0x3d122279, v148
	v_mul_f32_e32 v153, 0x3d122279, v149
	v_fmaak_f32 v152, v148, v152, 0x3f4c422a
	v_fmaak_f32 v153, v149, v153, 0x3f4c422a
	v_mul_f32_e32 v152, v148, v152
	v_mul_f32_e32 v153, v149, v153
	v_mul_f32_e32 v152, 0xc038aa3b, v152
	v_mul_f32_e32 v153, 0xc038aa3b, v153
	v_exp_f32_e32 v152, v152
	v_exp_f32_e32 v153, v153
	v_add_f32_e32 v152, 1.0, v152
	v_add_f32_e32 v153, 1.0, v153
	v_rcp_f32_e32 v152, v152
	v_rcp_f32_e32 v153, v153
	s_nop 0
	v_pk_mul_f32 v[148:149], v[148:149], v[152:153]
	s_nop 0
	v_pk_mul_f32 v[148:149], v[146:147], v[148:149]
	v_cvt_pk_bf16_f32 v146, v154, v155
	v_cvt_pk_bf16_f32 v147, v148, v149
	v_mov_b64_e32 v[148:149], s[12:13]
	v_mad_i64_i32 v[148:149], s[18:19], v150, s34, v[148:149]
	v_lshl_add_u64 v[148:149], v[182:183], 1, v[148:149]
	global_store_dwordx4 v[148:149], v[144:147], off
; __device__ __forceinline__ u32x4 pack8(const f32x4& v0, const f32x4& v1) { u32x4 w; w.x = cvt_pk_bf16(v0[0], v0[1]); w.y = cvt_pk_bf16(v0[2], v0[3]); w.z = cvt_pk_bf16(v1[0], v1[1]); w.w = cvt_pk_bf16(v1[2], v1[3]); return w; }
; __device__ __forceinline__ float dpp_ror1(float v) { return __int_as_float(__builtin_amdgcn_update_dpp(0, __float_as_int(v), 0x121, 0xf, 0xf, false)); }
; __device__ __forceinline__ float dpp_ror2(float v) { return __int_as_float(__builtin_amdgcn_update_dpp(0, __float_as_int(v), 0x122, 0xf, 0xf, false)); }
;     __device__ __forceinline__ void operator()(const f32x4 (&acc)[2][2][4][2], const Unit& u, int wr, int wc, int fr, int fq) const {
;     ...
;             for (int m = 0; m < 4; ++m) { const int r = ai * HALF + wr * 64 + m * 16 + fr, tk = 254 * i - 2 + r;
;                 f32x4 o[2];
; #pragma unroll
;                 for (int n = 0; n < 2; ++n) { f32x4 cur = acc[ai][0][m][n] * rn[ai][m]; if (tk < 0) cur = (f32x4){0.f, 0.f, 0.f, 0.f};
; #pragma unroll
;                     for (int j = 0; j < 4; ++j) { const float c1 = dpp_ror1(cur[j]), c2 = dpp_ror2(cur[j]);
;                         const float p1 = fr >= 1 ? c1 : pc1[n][j], p2 = fr >= 2 ? c2 : pc2[n][j]; pc1[n][j] = c1; pc2[n][j] = c2;
;                         const float cv = bb[n][j] + w0[n][j] * p2 + w1[n][j] * p1 + w2[n][j] * cur[j];
;                         o[n][j] = gelu_t(cv) * (acc[ai][1][m][n][j] * rn[ai][m]); } }
;                 if (r >= 2 && tk < 4096) *(u32x4*)(ACT + (size_t)(b * 4096 + tk) * 2816 + f0) = pack8(o[0], o[1]); }
.LBB0_299:
	s_or_b64 exec, exec, s[8:9]
	s_nop 0
	v_mul_f32_e32 v144, 0x4b800000, v164
	v_cndmask_b32_e64 v144, v164, v144, s[6:7]
	v_rsq_f32_e32 v144, v144
	v_add_u32_e32 v192, s77, v197
	v_mul_f32_e32 v145, 0x45800000, v144
	v_cndmask_b32_e64 v144, v144, v145, s[6:7]
	v_pk_mul_f32 v[140:141], v[140:141], v[144:145] op_sel_hi:[1,0]
	v_pk_mul_f32 v[142:143], v[142:143], v[144:145] op_sel_hi:[1,0]
	v_pk_mul_f32 v[146:147], v[136:137], v[144:145] op_sel_hi:[1,0]
	v_pk_mul_f32 v[136:137], v[138:139], v[144:145] op_sel_hi:[1,0]
	v_mov_b64_e32 v[138:139], v[146:147]
	v_cmp_gt_i32_e64 s[6:7], s83, v192
	v_mov_b32_dpp v149, v140 row_ror:1 row_mask:0xf bank_mask:0xf
	v_mov_b32_dpp v151, v140 row_ror:2 row_mask:0xf bank_mask:0xf
	v_mov_b32_dpp v150, v141 row_ror:1 row_mask:0xf bank_mask:0xf
	v_mov_b32_dpp v152, v141 row_ror:2 row_mask:0xf bank_mask:0xf
	v_mov_b32_dpp v153, v142 row_ror:1 row_mask:0xf bank_mask:0xf
	v_mov_b32_dpp v155, v142 row_ror:2 row_mask:0xf bank_mask:0xf
	v_mov_b32_dpp v154, v143 row_ror:1 row_mask:0xf bank_mask:0xf
	v_mov_b32_dpp v156, v143 row_ror:2 row_mask:0xf bank_mask:0xf
	v_mov_b32_dpp v157, v138 row_ror:1 row_mask:0xf bank_mask:0xf
	v_mov_b32_dpp v159, v138 row_ror:2 row_mask:0xf bank_mask:0xf
	v_mov_b32_dpp v158, v139 row_ror:1 row_mask:0xf bank_mask:0xf
	v_mov_b32_dpp v164, v139 row_ror:2 row_mask:0xf bank_mask:0xf
	v_mov_b32_dpp v145, v136 row_ror:1 row_mask:0xf bank_mask:0xf
	v_mov_b32_dpp v147, v136 row_ror:2 row_mask:0xf bank_mask:0xf
	v_mov_b32_dpp v146, v137 row_ror:1 row_mask:0xf bank_mask:0xf
	v_mov_b32_dpp v148, v137 row_ror:2 row_mask:0xf bank_mask:0xf
	s_and_b64 s[8:9], s[62:63], s[6:7]
	s_and_saveexec_b64 s[6:7], s[8:9]
	s_cbranch_execz .LBB0_301
	v_cndmask_b32_e64 v213, v226, v164, s[44:45]
	v_cndmask_b32_e64 v212, v225, v159, s[44:45]
	v_pk_fma_f32 v[212:213], v[72:73], v[212:213], v[76:77]
	v_cndmask_b32_e64 v215, v158, v224, s[42:43]
	v_cndmask_b32_e64 v214, v157, v223, s[42:43]
	v_pk_fma_f32 v[212:213], v[64:65], v[214:215], v[212:213]
	v_pk_mul_f32 v[128:129], v[128:129], v[144:145] op_sel_hi:[1,0]
	v_pk_fma_f32 v[138:139], v[138:139], v[68:69], v[212:213]
	v_pk_mul_f32 v[134:135], v[134:135], v[144:145] op_sel_hi:[1,0]
	v_mul_f32_e32 v212, 0x3d122279, v138
	v_mul_f32_e32 v213, 0x3d122279, v139
	v_fmaak_f32 v212, v138, v212, 0x3f4c422a
	v_fmaak_f32 v213, v139, v213, 0x3f4c422a
	v_mul_f32_e32 v212, v138, v212
	v_mul_f32_e32 v213, v139, v213
	v_mul_f32_e32 v212, 0xc038aa3b, v212
	v_mul_f32_e32 v213, 0xc038aa3b, v213
	v_exp_f32_e32 v212, v212
	v_exp_f32_e32 v213, v213
	v_pk_mul_f32 v[132:133], v[132:133], v[144:145] op_sel_hi:[1,0]
	v_pk_mul_f32 v[130:131], v[130:131], v[144:145] op_sel_hi:[1,0]
	v_add_f32_e32 v212, 1.0, v212
	v_add_f32_e32 v213, 1.0, v213
	v_rcp_f32_e32 v212, v212
	v_rcp_f32_e32 v213, v213
	s_nop 0
	v_pk_mul_f32 v[138:139], v[138:139], v[212:213]
	s_nop 0
	v_pk_mul_f32 v[138:139], v[128:129], v[138:139]
	v_cndmask_b32_e64 v129, v222, v156, s[44:45]
	v_cndmask_b32_e64 v128, v221, v155, s[44:45]
	v_pk_fma_f32 v[128:129], v[98:99], v[128:129], v[102:103]
	v_cndmask_b32_e64 v213, v154, v220, s[42:43]
	v_cndmask_b32_e64 v212, v153, v219, s[42:43]
	v_pk_fma_f32 v[128:129], v[90:91], v[212:213], v[128:129]
	s_nop 0
	v_pk_fma_f32 v[128:129], v[142:143], v[94:95], v[128:129]
	s_nop 0
	v_mul_f32_e32 v142, 0x3d122279, v128
	v_mul_f32_e32 v143, 0x3d122279, v129
	v_fmaak_f32 v142, v128, v142, 0x3f4c422a
	v_fmaak_f32 v143, v129, v143, 0x3f4c422a
	v_mul_f32_e32 v142, v128, v142
	v_mul_f32_e32 v143, v129, v143
	v_mul_f32_e32 v142, 0xc038aa3b, v142
	v_mul_f32_e32 v143, 0xc038aa3b, v143
	v_exp_f32_e32 v142, v142
	v_exp_f32_e32 v143, v143
	v_add_f32_e32 v142, 1.0, v142
	v_add_f32_e32 v143, 1.0, v143
	v_rcp_f32_e32 v142, v142
	v_rcp_f32_e32 v143, v143
	s_nop 0
	v_pk_mul_f32 v[128:129], v[128:129], v[142:143]
	s_nop 0
	v_pk_mul_f32 v[134:135], v[134:135], v[128:129]
	v_cndmask_b32_e64 v129, v195, v152, s[44:45]
	v_cndmask_b32_e64 v128, v194, v151, s[44:45]
	v_pk_fma_f32 v[128:129], v[96:97], v[128:129], v[100:101]
	v_cndmask_b32_e64 v143, v150, v193, s[42:43]
	v_cndmask_b32_e64 v142, v149, v165, s[42:43]
	v_pk_fma_f32 v[128:129], v[88:89], v[142:143], v[128:129]
	s_nop 0
	v_pk_fma_f32 v[128:129], v[140:141], v[92:93], v[128:129]
	s_nop 0
	v_mul_f32_e32 v140, 0x3d122279, v128
	v_mul_f32_e32 v141, 0x3d122279, v129
	v_fmaak_f32 v140, v128, v140, 0x3f4c422a
	v_fmaak_f32 v141, v129, v141, 0x3f4c422a
	v_mul_f32_e32 v140, v128, v140
	v_mul_f32_e32 v141, v129, v141
	v_mul_f32_e32 v140, 0xc038aa3b, v140
	v_mul_f32_e32 v141, 0xc038aa3b, v141
	v_exp_f32_e32 v140, v140
	v_exp_f32_e32 v141, v141
	v_add_f32_e32 v140, 1.0, v140
	v_add_f32_e32 v141, 1.0, v141
	v_rcp_f32_e32 v140, v140
	v_rcp_f32_e32 v141, v141
	s_nop 0
	v_pk_mul_f32 v[128:129], v[128:129], v[140:141]
	s_nop 0
	v_pk_mul_f32 v[128:129], v[132:133], v[128:129]
	v_cndmask_b32_e64 v133, v163, v148, s[44:45]
	v_cndmask_b32_e64 v132, v162, v147, s[44:45]
	v_cndmask_b32_e64 v141, v146, v161, s[42:43]
	v_cndmask_b32_e64 v140, v145, v160, s[42:43]
	v_pk_fma_f32 v[132:133], v[74:75], v[132:133], v[78:79]
	v_cvt_pk_bf16_f32 v128, v128, v129
	v_pk_fma_f32 v[132:133], v[66:67], v[140:141], v[132:133]
	v_cvt_pk_bf16_f32 v129, v134, v135
	v_pk_fma_f32 v[132:133], v[136:137], v[70:71], v[132:133]
	v_add_u32_e32 v134, s71, v192
	v_mul_f32_e32 v136, 0x3d122279, v132
	v_mul_f32_e32 v137, 0x3d122279, v133
	v_fmaak_f32 v136, v132, v136, 0x3f4c422a
	v_fmaak_f32 v137, v133, v137, 0x3f4c422a
	v_mul_f32_e32 v136, v132, v136
	v_mul_f32_e32 v137, v133, v137
	v_mul_f32_e32 v136, 0xc038aa3b, v136
	v_mul_f32_e32 v137, 0xc038aa3b, v137
	v_exp_f32_e32 v136, v136
	v_exp_f32_e32 v137, v137
	v_add_f32_e32 v136, 1.0, v136
	v_add_f32_e32 v137, 1.0, v137
	v_rcp_f32_e32 v136, v136
	v_rcp_f32_e32 v137, v137
	s_nop 0
	v_pk_mul_f32 v[132:133], v[132:133], v[136:137]
	s_nop 0
	v_pk_mul_f32 v[132:133], v[130:131], v[132:133]
	v_cvt_pk_bf16_f32 v130, v138, v139
	v_cvt_pk_bf16_f32 v131, v132, v133
	v_mov_b64_e32 v[132:133], s[12:13]
	v_mad_i64_i32 v[132:133], s[8:9], v134, s34, v[132:133]
	v_lshl_add_u64 v[132:133], v[182:183], 1, v[132:133]
	global_store_dwordx4 v[132:133], v[128:131], off
; __device__ __forceinline__ u32x4 pack8(const f32x4& v0, const f32x4& v1) { u32x4 w; w.x = cvt_pk_bf16(v0[0], v0[1]); w.y = cvt_pk_bf16(v0[2], v0[3]); w.z = cvt_pk_bf16(v1[0], v1[1]); w.w = cvt_pk_bf16(v1[2], v1[3]); return w; }
; __device__ __forceinline__ float dpp_ror1(float v) { return __int_as_float(__builtin_amdgcn_update_dpp(0, __float_as_int(v), 0x121, 0xf, 0xf, false)); }
; __device__ __forceinline__ float dpp_ror2(float v) { return __int_as_float(__builtin_amdgcn_update_dpp(0, __float_as_int(v), 0x122, 0xf, 0xf, false)); }
;     __device__ __forceinline__ void operator()(const f32x4 (&acc)[2][2][4][2], const Unit& u, int wr, int wc, int fr, int fq) const {
;     ...
;             for (int m = 0; m < 4; ++m) { const int r = ai * HALF + wr * 64 + m * 16 + fr, tk = 254 * i - 2 + r;
;                 f32x4 o[2];
; #pragma unroll
;                 for (int n = 0; n < 2; ++n) { f32x4 cur = acc[ai][0][m][n] * rn[ai][m]; if (tk < 0) cur = (f32x4){0.f, 0.f, 0.f, 0.f};
; #pragma unroll
;                     for (int j = 0; j < 4; ++j) { const float c1 = dpp_ror1(cur[j]), c2 = dpp_ror2(cur[j]);
;                         const float p1 = fr >= 1 ? c1 : pc1[n][j], p2 = fr >= 2 ? c2 : pc2[n][j]; pc1[n][j] = c1; pc2[n][j] = c2;
;                         const float cv = bb[n][j] + w0[n][j] * p2 + w1[n][j] * p1 + w2[n][j] * cur[j];
;                         o[n][j] = gelu_t(cv) * (acc[ai][1][m][n][j] * rn[ai][m]); } }
;                 if (r >= 2 && tk < 4096) *(u32x4*)(ACT + (size_t)(b * 4096 + tk) * 2816 + f0) = pack8(o[0], o[1]); }
.LBB0_301:
	s_or_b64 exec, exec, s[6:7]
	s_nop 0
	v_mul_f32_e32 v128, 0x4b800000, v187
	v_cndmask_b32_e64 v128, v187, v128, s[4:5]
	v_rsq_f32_e32 v128, v128
	v_add_u32_e32 v160, s77, v198
	v_mul_f32_e32 v129, 0x45800000, v128
	v_cndmask_b32_e64 v128, v128, v129, s[4:5]
	v_pk_mul_f32 v[124:125], v[124:125], v[128:129] op_sel_hi:[1,0]
	v_pk_mul_f32 v[126:127], v[126:127], v[128:129] op_sel_hi:[1,0]
	v_pk_mul_f32 v[130:131], v[120:121], v[128:129] op_sel_hi:[1,0]
	v_pk_mul_f32 v[120:121], v[122:123], v[128:129] op_sel_hi:[1,0]
	v_mov_b64_e32 v[122:123], v[130:131]
	v_cmp_gt_i32_e64 s[4:5], s83, v160
	v_mov_b32_dpp v133, v124 row_ror:1 row_mask:0xf bank_mask:0xf
	v_mov_b32_dpp v135, v124 row_ror:2 row_mask:0xf bank_mask:0xf
	v_mov_b32_dpp v134, v125 row_ror:1 row_mask:0xf bank_mask:0xf
	v_mov_b32_dpp v136, v125 row_ror:2 row_mask:0xf bank_mask:0xf
	v_mov_b32_dpp v137, v126 row_ror:1 row_mask:0xf bank_mask:0xf
	v_mov_b32_dpp v139, v126 row_ror:2 row_mask:0xf bank_mask:0xf
	v_mov_b32_dpp v138, v127 row_ror:1 row_mask:0xf bank_mask:0xf
	v_mov_b32_dpp v140, v127 row_ror:2 row_mask:0xf bank_mask:0xf
	v_mov_b32_dpp v141, v122 row_ror:1 row_mask:0xf bank_mask:0xf
	v_mov_b32_dpp v143, v122 row_ror:2 row_mask:0xf bank_mask:0xf
	v_mov_b32_dpp v142, v123 row_ror:1 row_mask:0xf bank_mask:0xf
	v_mov_b32_dpp v144, v123 row_ror:2 row_mask:0xf bank_mask:0xf
	v_mov_b32_dpp v129, v120 row_ror:1 row_mask:0xf bank_mask:0xf
	v_mov_b32_dpp v131, v120 row_ror:2 row_mask:0xf bank_mask:0xf
	v_mov_b32_dpp v130, v121 row_ror:1 row_mask:0xf bank_mask:0xf
	v_mov_b32_dpp v132, v121 row_ror:2 row_mask:0xf bank_mask:0xf
	s_and_b64 s[6:7], s[62:63], s[4:5]
	s_and_saveexec_b64 s[4:5], s[6:7]
	s_cbranch_execz .LBB0_303
	v_cndmask_b32_e64 v163, v164, v144, s[44:45]
	v_cndmask_b32_e64 v162, v159, v143, s[44:45]
	v_pk_fma_f32 v[162:163], v[72:73], v[162:163], v[76:77]
	v_cndmask_b32_e64 v159, v142, v158, s[42:43]
	v_cndmask_b32_e64 v158, v141, v157, s[42:43]
	v_pk_fma_f32 v[158:159], v[64:65], v[158:159], v[162:163]
	v_pk_mul_f32 v[112:113], v[112:113], v[128:129] op_sel_hi:[1,0]
	v_pk_fma_f32 v[122:123], v[122:123], v[68:69], v[158:159]
	v_pk_mul_f32 v[118:119], v[118:119], v[128:129] op_sel_hi:[1,0]
	v_mul_f32_e32 v157, 0x3d122279, v122
	v_fmaak_f32 v157, v122, v157, 0x3f4c422a
	v_mul_f32_e32 v157, v122, v157
	v_mul_f32_e32 v157, 0xc038aa3b, v157
	v_exp_f32_e32 v157, v157
	v_pk_mul_f32 v[116:117], v[116:117], v[128:129] op_sel_hi:[1,0]
	v_pk_mul_f32 v[114:115], v[114:115], v[128:129] op_sel_hi:[1,0]
	v_add_f32_e32 v157, 1.0, v157
	v_rcp_f32_e32 v158, v157
	v_mul_f32_e32 v157, 0x3d122279, v123
	v_fmaak_f32 v157, v123, v157, 0x3f4c422a
	v_mul_f32_e32 v157, v123, v157
	v_mul_f32_e32 v157, 0xc038aa3b, v157
	v_exp_f32_e32 v157, v157
	s_nop 0
	v_add_f32_e32 v157, 1.0, v157
	v_rcp_f32_e32 v159, v157
	s_nop 0
	v_pk_mul_f32 v[122:123], v[122:123], v[158:159]
	s_nop 0
	v_pk_mul_f32 v[122:123], v[112:113], v[122:123]
	v_cndmask_b32_e64 v113, v156, v140, s[44:45]
	v_cndmask_b32_e64 v112, v155, v139, s[44:45]
	v_pk_fma_f32 v[112:113], v[98:99], v[112:113], v[102:103]
	v_cndmask_b32_e64 v155, v138, v154, s[42:43]
	v_cndmask_b32_e64 v154, v137, v153, s[42:43]
	v_pk_fma_f32 v[112:113], v[90:91], v[154:155], v[112:113]
	s_nop 0
	v_pk_fma_f32 v[112:113], v[126:127], v[94:95], v[112:113]
	s_nop 0
	v_mul_f32_e32 v126, 0x3d122279, v112
	v_mul_f32_e32 v127, 0x3d122279, v113
	v_fmaak_f32 v126, v112, v126, 0x3f4c422a
	v_fmaak_f32 v127, v113, v127, 0x3f4c422a
	v_mul_f32_e32 v126, v112, v126
	v_mul_f32_e32 v127, v113, v127
	v_mul_f32_e32 v126, 0xc038aa3b, v126
	v_mul_f32_e32 v127, 0xc038aa3b, v127
	v_exp_f32_e32 v126, v126
	v_exp_f32_e32 v127, v127
	v_add_f32_e32 v126, 1.0, v126
	v_add_f32_e32 v127, 1.0, v127
	v_rcp_f32_e32 v126, v126
	v_rcp_f32_e32 v127, v127
	s_nop 0
	v_pk_mul_f32 v[112:113], v[112:113], v[126:127]
	s_nop 0
	v_pk_mul_f32 v[118:119], v[118:119], v[112:113]
	v_cndmask_b32_e64 v113, v152, v136, s[44:45]
	v_cndmask_b32_e64 v112, v151, v135, s[44:45]
	v_pk_fma_f32 v[112:113], v[96:97], v[112:113], v[100:101]
	v_cndmask_b32_e64 v127, v134, v150, s[42:43]
	v_cndmask_b32_e64 v126, v133, v149, s[42:43]
	v_pk_fma_f32 v[112:113], v[88:89], v[126:127], v[112:113]
	s_nop 0
	v_pk_fma_f32 v[112:113], v[124:125], v[92:93], v[112:113]
	s_nop 0
	v_mul_f32_e32 v124, 0x3d122279, v112
	v_mul_f32_e32 v125, 0x3d122279, v113
	v_fmaak_f32 v124, v112, v124, 0x3f4c422a
	v_fmaak_f32 v125, v113, v125, 0x3f4c422a
	v_mul_f32_e32 v124, v112, v124
	v_mul_f32_e32 v125, v113, v125
	v_mul_f32_e32 v124, 0xc038aa3b, v124
	v_mul_f32_e32 v125, 0xc038aa3b, v125
	v_exp_f32_e32 v124, v124
	v_exp_f32_e32 v125, v125
	v_add_f32_e32 v124, 1.0, v124
	v_add_f32_e32 v125, 1.0, v125
	v_rcp_f32_e32 v124, v124
	v_rcp_f32_e32 v125, v125
	s_nop 0
	v_pk_mul_f32 v[112:113], v[112:113], v[124:125]
	s_nop 0
	v_pk_mul_f32 v[112:113], v[116:117], v[112:113]
	v_cndmask_b32_e64 v117, v148, v132, s[44:45]
	v_cndmask_b32_e64 v116, v147, v131, s[44:45]
	v_cndmask_b32_e64 v125, v130, v146, s[42:43]
	v_cndmask_b32_e64 v124, v129, v145, s[42:43]
	v_pk_fma_f32 v[116:117], v[74:75], v[116:117], v[78:79]
	v_cvt_pk_bf16_f32 v112, v112, v113
	v_pk_fma_f32 v[116:117], v[66:67], v[124:125], v[116:117]
	v_cvt_pk_bf16_f32 v113, v118, v119
	v_pk_fma_f32 v[116:117], v[120:121], v[70:71], v[116:117]
	v_add_u32_e32 v118, s71, v160
	v_mul_f32_e32 v120, 0x3d122279, v116
	v_mul_f32_e32 v121, 0x3d122279, v117
	v_fmaak_f32 v120, v116, v120, 0x3f4c422a
	v_fmaak_f32 v121, v117, v121, 0x3f4c422a
	v_mul_f32_e32 v120, v116, v120
	v_mul_f32_e32 v121, v117, v121
	v_mul_f32_e32 v120, 0xc038aa3b, v120
	v_mul_f32_e32 v121, 0xc038aa3b, v121
	v_exp_f32_e32 v120, v120
	v_exp_f32_e32 v121, v121
	v_add_f32_e32 v120, 1.0, v120
	v_add_f32_e32 v121, 1.0, v121
	v_rcp_f32_e32 v120, v120
	v_rcp_f32_e32 v121, v121
	s_nop 0
	v_pk_mul_f32 v[116:117], v[116:117], v[120:121]
	s_nop 0
	v_pk_mul_f32 v[116:117], v[114:115], v[116:117]
	v_cvt_pk_bf16_f32 v114, v122, v123
	v_cvt_pk_bf16_f32 v115, v116, v117
	v_mov_b64_e32 v[116:117], s[12:13]
	v_mad_i64_i32 v[116:117], s[6:7], v118, s34, v[116:117]
	v_lshl_add_u64 v[116:117], v[182:183], 1, v[116:117]
	global_store_dwordx4 v[116:117], v[112:115], off
; __device__ __forceinline__ u32x4 pack8(const f32x4& v0, const f32x4& v1) { u32x4 w; w.x = cvt_pk_bf16(v0[0], v0[1]); w.y = cvt_pk_bf16(v0[2], v0[3]); w.z = cvt_pk_bf16(v1[0], v1[1]); w.w = cvt_pk_bf16(v1[2], v1[3]); return w; }
; __device__ __forceinline__ float dpp_ror1(float v) { return __int_as_float(__builtin_amdgcn_update_dpp(0, __float_as_int(v), 0x121, 0xf, 0xf, false)); }
; __device__ __forceinline__ float dpp_ror2(float v) { return __int_as_float(__builtin_amdgcn_update_dpp(0, __float_as_int(v), 0x122, 0xf, 0xf, false)); }
;     __device__ __forceinline__ void operator()(const f32x4 (&acc)[2][2][4][2], const Unit& u, int wr, int wc, int fr, int fq) const {
;     ...
;             for (int m = 0; m < 4; ++m) { const int r = ai * HALF + wr * 64 + m * 16 + fr, tk = 254 * i - 2 + r;
;                 f32x4 o[2];
; #pragma unroll
;                 for (int n = 0; n < 2; ++n) { f32x4 cur = acc[ai][0][m][n] * rn[ai][m]; if (tk < 0) cur = (f32x4){0.f, 0.f, 0.f, 0.f};
; #pragma unroll
;                     for (int j = 0; j < 4; ++j) { const float c1 = dpp_ror1(cur[j]), c2 = dpp_ror2(cur[j]);
;                         const float p1 = fr >= 1 ? c1 : pc1[n][j], p2 = fr >= 2 ? c2 : pc2[n][j]; pc1[n][j] = c1; pc2[n][j] = c2;
;                         const float cv = bb[n][j] + w0[n][j] * p2 + w1[n][j] * p1 + w2[n][j] * cur[j];
;                         o[n][j] = gelu_t(cv) * (acc[ai][1][m][n][j] * rn[ai][m]); } }
;                 if (r >= 2 && tk < 4096) *(u32x4*)(ACT + (size_t)(b * 4096 + tk) * 2816 + f0) = pack8(o[0], o[1]); }
.LBB0_303:
	s_or_b64 exec, exec, s[4:5]
	s_nop 0
	v_add_u32_e32 v112, s77, v199
	v_pk_mul_f32 v[110:111], v[110:111], v[186:187] op_sel_hi:[1,0]
	v_pk_mul_f32 v[108:109], v[108:109], v[186:187] op_sel_hi:[1,0]
	v_pk_mul_f32 v[114:115], v[106:107], v[186:187] op_sel_hi:[1,0]
	v_pk_mul_f32 v[104:105], v[104:105], v[186:187] op_sel_hi:[1,0]
	v_mov_b64_e32 v[106:107], v[104:105]
	v_mov_b64_e32 v[104:105], v[114:115]
	v_cmp_gt_i32_e64 s[4:5], s83, v112
	v_mov_b32_dpp v117, v108 row_ror:1 row_mask:0xf bank_mask:0xf
	v_mov_b32_dpp v119, v108 row_ror:2 row_mask:0xf bank_mask:0xf
	v_mov_b32_dpp v118, v109 row_ror:1 row_mask:0xf bank_mask:0xf
	v_mov_b32_dpp v120, v109 row_ror:2 row_mask:0xf bank_mask:0xf
	v_mov_b32_dpp v121, v110 row_ror:1 row_mask:0xf bank_mask:0xf
	v_mov_b32_dpp v123, v110 row_ror:2 row_mask:0xf bank_mask:0xf
	v_mov_b32_dpp v122, v111 row_ror:1 row_mask:0xf bank_mask:0xf
	v_mov_b32_dpp v124, v111 row_ror:2 row_mask:0xf bank_mask:0xf
	v_mov_b32_dpp v125, v106 row_ror:1 row_mask:0xf bank_mask:0xf
	v_mov_b32_dpp v127, v106 row_ror:2 row_mask:0xf bank_mask:0xf
	v_mov_b32_dpp v126, v107 row_ror:1 row_mask:0xf bank_mask:0xf
	v_mov_b32_dpp v128, v107 row_ror:2 row_mask:0xf bank_mask:0xf
	v_mov_b32_dpp v113, v104 row_ror:1 row_mask:0xf bank_mask:0xf
	v_mov_b32_dpp v115, v104 row_ror:2 row_mask:0xf bank_mask:0xf
	v_mov_b32_dpp v114, v105 row_ror:1 row_mask:0xf bank_mask:0xf
	v_mov_b32_dpp v116, v105 row_ror:2 row_mask:0xf bank_mask:0xf
	s_and_b64 s[6:7], s[62:63], s[4:5]
	s_and_saveexec_b64 s[4:5], s[6:7]
	s_cbranch_execz .LBB0_305
	v_cndmask_b32_e64 v145, v144, v128, s[44:45]
	v_cndmask_b32_e64 v144, v143, v127, s[44:45]
	v_pk_fma_f32 v[144:145], v[72:73], v[144:145], v[76:77]
	v_cndmask_b32_e64 v127, v126, v142, s[42:43]
	v_cndmask_b32_e64 v126, v125, v141, s[42:43]
	v_pk_fma_f32 v[126:127], v[64:65], v[126:127], v[144:145]
	v_pk_mul_f32 v[80:81], v[80:81], v[186:187] op_sel_hi:[1,0]
	v_pk_fma_f32 v[106:107], v[106:107], v[68:69], v[126:127]
	v_pk_mul_f32 v[86:87], v[86:87], v[186:187] op_sel_hi:[1,0]
	v_mul_f32_e32 v125, 0x3d122279, v106
	v_fmaak_f32 v125, v106, v125, 0x3f4c422a
	v_mul_f32_e32 v125, v106, v125
	v_mul_f32_e32 v125, 0xc038aa3b, v125
	v_exp_f32_e32 v125, v125
	v_pk_mul_f32 v[84:85], v[84:85], v[186:187] op_sel_hi:[1,0]
	v_pk_mul_f32 v[82:83], v[82:83], v[186:187] op_sel_hi:[1,0]
	v_add_f32_e32 v125, 1.0, v125
	v_rcp_f32_e32 v126, v125
	v_mul_f32_e32 v125, 0x3d122279, v107
	v_fmaak_f32 v125, v107, v125, 0x3f4c422a
	v_mul_f32_e32 v125, v107, v125
	v_mul_f32_e32 v125, 0xc038aa3b, v125
	v_exp_f32_e32 v125, v125
	s_nop 0
	v_add_f32_e32 v125, 1.0, v125
	v_rcp_f32_e32 v127, v125
	s_nop 0
	v_pk_mul_f32 v[106:107], v[106:107], v[126:127]
	s_nop 0
	v_pk_mul_f32 v[106:107], v[80:81], v[106:107]
	v_cndmask_b32_e64 v81, v140, v124, s[44:45]
	v_cndmask_b32_e64 v80, v139, v123, s[44:45]
	v_pk_fma_f32 v[80:81], v[98:99], v[80:81], v[102:103]
	v_cndmask_b32_e64 v123, v122, v138, s[42:43]
	v_cndmask_b32_e64 v122, v121, v137, s[42:43]
	v_pk_fma_f32 v[80:81], v[90:91], v[122:123], v[80:81]
	s_nop 0
	v_pk_fma_f32 v[80:81], v[110:111], v[94:95], v[80:81]
	s_nop 0
	v_mul_f32_e32 v110, 0x3d122279, v80
	v_mul_f32_e32 v111, 0x3d122279, v81
	v_fmaak_f32 v110, v80, v110, 0x3f4c422a
	v_fmaak_f32 v111, v81, v111, 0x3f4c422a
	v_mul_f32_e32 v110, v80, v110
	v_mul_f32_e32 v111, v81, v111
	v_mul_f32_e32 v110, 0xc038aa3b, v110
	v_mul_f32_e32 v111, 0xc038aa3b, v111
	v_exp_f32_e32 v110, v110
	v_exp_f32_e32 v111, v111
	v_add_f32_e32 v110, 1.0, v110
	v_add_f32_e32 v111, 1.0, v111
	v_rcp_f32_e32 v110, v110
	v_rcp_f32_e32 v111, v111
	s_nop 0
	v_pk_mul_f32 v[80:81], v[80:81], v[110:111]
	s_nop 0
	v_pk_mul_f32 v[86:87], v[86:87], v[80:81]
	v_cndmask_b32_e64 v81, v136, v120, s[44:45]
	v_cndmask_b32_e64 v80, v135, v119, s[44:45]
	v_pk_fma_f32 v[80:81], v[96:97], v[80:81], v[100:101]
	v_cndmask_b32_e64 v111, v118, v134, s[42:43]
	v_cndmask_b32_e64 v110, v117, v133, s[42:43]
	v_pk_fma_f32 v[80:81], v[88:89], v[110:111], v[80:81]
	s_nop 0
	v_pk_fma_f32 v[80:81], v[108:109], v[92:93], v[80:81]
	s_nop 0
	v_mul_f32_e32 v108, 0x3d122279, v80
	v_mul_f32_e32 v109, 0x3d122279, v81
	v_fmaak_f32 v108, v80, v108, 0x3f4c422a
	v_fmaak_f32 v109, v81, v109, 0x3f4c422a
	v_mul_f32_e32 v108, v80, v108
	v_mul_f32_e32 v109, v81, v109
	v_mul_f32_e32 v108, 0xc038aa3b, v108
	v_mul_f32_e32 v109, 0xc038aa3b, v109
	v_exp_f32_e32 v108, v108
	v_exp_f32_e32 v109, v109
	v_add_f32_e32 v108, 1.0, v108
	v_add_f32_e32 v109, 1.0, v109
	v_rcp_f32_e32 v108, v108
	v_rcp_f32_e32 v109, v109
	s_nop 0
	v_pk_mul_f32 v[80:81], v[80:81], v[108:109]
	s_nop 0
	v_pk_mul_f32 v[80:81], v[84:85], v[80:81]
	v_cndmask_b32_e64 v85, v132, v116, s[44:45]
	v_cndmask_b32_e64 v84, v131, v115, s[44:45]
	v_cndmask_b32_e64 v109, v114, v130, s[42:43]
	v_cndmask_b32_e64 v108, v113, v129, s[42:43]
	v_pk_fma_f32 v[84:85], v[74:75], v[84:85], v[78:79]
	v_cvt_pk_bf16_f32 v80, v80, v81
	v_pk_fma_f32 v[84:85], v[66:67], v[108:109], v[84:85]
	v_cvt_pk_bf16_f32 v81, v86, v87
	v_pk_fma_f32 v[84:85], v[104:105], v[70:71], v[84:85]
	v_add_u32_e32 v86, s71, v112
	v_mul_f32_e32 v104, 0x3d122279, v84
	v_mul_f32_e32 v105, 0x3d122279, v85
	v_fmaak_f32 v104, v84, v104, 0x3f4c422a
	v_fmaak_f32 v105, v85, v105, 0x3f4c422a
	v_mul_f32_e32 v104, v84, v104
	v_mul_f32_e32 v105, v85, v105
	v_mul_f32_e32 v104, 0xc038aa3b, v104
	v_mul_f32_e32 v105, 0xc038aa3b, v105
	v_exp_f32_e32 v104, v104
	v_exp_f32_e32 v105, v105
	v_add_f32_e32 v104, 1.0, v104
	v_add_f32_e32 v105, 1.0, v105
	v_rcp_f32_e32 v104, v104
	v_rcp_f32_e32 v105, v105
	s_nop 0
	v_pk_mul_f32 v[84:85], v[84:85], v[104:105]
	s_nop 0
	v_pk_mul_f32 v[84:85], v[82:83], v[84:85]
	v_cvt_pk_bf16_f32 v82, v106, v107
	v_cvt_pk_bf16_f32 v83, v84, v85
	v_mov_b64_e32 v[84:85], s[12:13]
	v_mad_i64_i32 v[84:85], s[6:7], v86, s34, v[84:85]
	v_lshl_add_u64 v[84:85], v[182:183], 1, v[84:85]
	global_store_dwordx4 v[84:85], v[80:83], off
; #define PG8_LAS __attribute__((address_space(3)))
; __device__ __forceinline__ u32x4 pack8(const f32x4& v0, const f32x4& v1) { u32x4 w; w.x = cvt_pk_bf16(v0[0], v0[1]); w.y = cvt_pk_bf16(v0[2], v0[3]); w.z = cvt_pk_bf16(v1[0], v1[1]); w.w = cvt_pk_bf16(v1[2], v1[3]); return w; }
; __device__ __forceinline__ float dpp_ror1(float v) { return __int_as_float(__builtin_amdgcn_update_dpp(0, __float_as_int(v), 0x121, 0xf, 0xf, false)); }
; __device__ __forceinline__ float dpp_ror2(float v) { return __int_as_float(__builtin_amdgcn_update_dpp(0, __float_as_int(v), 0x122, 0xf, 0xf, false)); }
;     __device__ __forceinline__ void operator()(const f32x4 (&acc)[2][2][4][2], const Unit& u, int wr, int wc, int fr, int fq) const {
;     ...
;         for (int ai = 0; ai < 2; ++ai) {
;             const int blk = ai * 2 + wr;
;             f32x4 pc1[2], pc2[2];
; #pragma unroll
;             for (int n = 0; n < 2; ++n) { f32x4 hv = {0.f, 0.f, 0.f, 0.f};
;                 if (blk > 0 && fr >= 14) hv = *(const PG8_LAS f32x4*)(halo + ((blk - 1) * 2 + (fr - 14)) * 128 + fl + 4 * n);
; #pragma unroll
;                 for (int j = 0; j < 4; ++j) { pc1[n][j] = dpp_ror1(hv[j]); pc2[n][j] = dpp_ror2(hv[j]); } }
; #pragma unroll
;             for (int m = 0; m < 4; ++m) { const int r = ai * HALF + wr * 64 + m * 16 + fr, tk = 254 * i - 2 + r;
;                 f32x4 o[2];
; #pragma unroll
;                 for (int n = 0; n < 2; ++n) { f32x4 cur = acc[ai][0][m][n] * rn[ai][m]; if (tk < 0) cur = (f32x4){0.f, 0.f, 0.f, 0.f};
; #pragma unroll
;                     for (int j = 0; j < 4; ++j) { const float c1 = dpp_ror1(cur[j]), c2 = dpp_ror2(cur[j]);
;                         const float p1 = fr >= 1 ? c1 : pc1[n][j], p2 = fr >= 2 ? c2 : pc2[n][j]; pc1[n][j] = c1; pc2[n][j] = c2;
;                         const float cv = bb[n][j] + w0[n][j] * p2 + w1[n][j] * p1 + w2[n][j] * cur[j];
;                         o[n][j] = gelu_t(cv) * (acc[ai][1][m][n][j] * rn[ai][m]); } }
;                 if (r >= 2 && tk < 4096) *(u32x4*)(ACT + (size_t)(b * 4096 + tk) * 2816 + f0) = pack8(o[0], o[1]); }
.LBB0_305:
	s_or_b64 exec, exec, s[4:5]
	s_nop 0
	v_mov_b32_e32 v80, 0
	v_mov_b32_e32 v82, 0
	v_mov_b32_e32 v83, 0
	v_mov_b32_e32 v84, 0
	v_mov_b32_e32 v85, 0
	s_and_saveexec_b64 s[4:5], s[64:65]
	ds_read_b128 v[82:85], v207
	s_or_b64 exec, exec, s[4:5]
	s_waitcnt lgkmcnt(0)
	v_mov_b32_dpp v115, v82 row_ror:1 row_mask:0xf bank_mask:0xf
	v_mov_b32_dpp v120, v82 row_ror:2 row_mask:0xf bank_mask:0xf
	v_mov_b32_dpp v117, v83 row_ror:1 row_mask:0xf bank_mask:0xf
	v_mov_b32_dpp v122, v83 row_ror:2 row_mask:0xf bank_mask:0xf
	v_mov_b32_dpp v123, v84 row_ror:1 row_mask:0xf bank_mask:0xf
	v_mov_b32_dpp v125, v84 row_ror:2 row_mask:0xf bank_mask:0xf
	v_mov_b32_dpp v124, v85 row_ror:1 row_mask:0xf bank_mask:0xf
	v_mov_b32_dpp v126, v85 row_ror:2 row_mask:0xf bank_mask:0xf
	v_mov_b32_e32 v81, 0
	v_mov_b32_e32 v82, 0
	v_mov_b32_e32 v83, 0
	s_and_saveexec_b64 s[4:5], s[64:65]
	ds_read_b128 v[80:83], v207 offset:16
	s_or_b64 exec, exec, s[4:5]
	v_pk_add_f32 v[84:85], v[188:189], v[190:191]
	v_add_u32_e32 v114, s77, v200
	v_pk_fma_f32 v[84:85], v[84:85], s[78:79], v[210:211] op_sel_hi:[1,0,0]
	v_mul_f32_e32 v86, 0x4b800000, v85
	v_cmp_gt_f32_e64 s[6:7], s39, v85
	s_nop 1
	v_cndmask_b32_e64 v85, v85, v86, s[6:7]
	v_rsq_f32_e32 v85, v85
	s_waitcnt lgkmcnt(0)
	v_mov_b32_dpp v127, v80 row_ror:1 row_mask:0xf bank_mask:0xf
	v_mov_b32_dpp v129, v80 row_ror:2 row_mask:0xf bank_mask:0xf
	v_mul_f32_e32 v86, 0x45800000, v85
	v_cndmask_b32_e64 v86, v85, v86, s[6:7]
	v_pk_mul_f32 v[60:61], v[60:61], v[86:87] op_sel_hi:[1,0]
	v_pk_mul_f32 v[62:63], v[62:63], v[86:87] op_sel_hi:[1,0]
	s_nop 0
	v_mov_b32_dpp v128, v81 row_ror:1 row_mask:0xf bank_mask:0xf
	v_mov_b32_dpp v130, v81 row_ror:2 row_mask:0xf bank_mask:0xf
	v_mov_b32_dpp v87, v61 row_ror:1 row_mask:0xf bank_mask:0xf
	v_pk_mul_f32 v[80:81], v[56:57], v[86:87] op_sel_hi:[1,0]
	v_pk_mul_f32 v[56:57], v[58:59], v[86:87] op_sel_hi:[1,0]
	v_mov_b32_dpp v116, v82 row_ror:1 row_mask:0xf bank_mask:0xf
	v_mov_b32_dpp v119, v82 row_ror:2 row_mask:0xf bank_mask:0xf
	v_mov_b32_dpp v118, v83 row_ror:1 row_mask:0xf bank_mask:0xf
	v_mov_b32_dpp v121, v83 row_ror:2 row_mask:0xf bank_mask:0xf
	v_mov_b64_e32 v[58:59], v[80:81]
	v_cmp_gt_i32_e64 s[6:7], s83, v114
	v_cmp_gt_f32_e64 s[4:5], s39, v84
	v_mov_b32_dpp v85, v60 row_ror:1 row_mask:0xf bank_mask:0xf
	v_mov_b32_dpp v104, v60 row_ror:2 row_mask:0xf bank_mask:0xf
	v_mov_b32_dpp v105, v61 row_ror:2 row_mask:0xf bank_mask:0xf
	v_mov_b32_dpp v106, v62 row_ror:1 row_mask:0xf bank_mask:0xf
	v_mov_b32_dpp v108, v62 row_ror:2 row_mask:0xf bank_mask:0xf
	v_mov_b32_dpp v107, v63 row_ror:1 row_mask:0xf bank_mask:0xf
	v_mov_b32_dpp v109, v63 row_ror:2 row_mask:0xf bank_mask:0xf
	v_mov_b32_dpp v110, v58 row_ror:1 row_mask:0xf bank_mask:0xf
	v_mov_b32_dpp v112, v58 row_ror:2 row_mask:0xf bank_mask:0xf
	v_mov_b32_dpp v111, v59 row_ror:1 row_mask:0xf bank_mask:0xf
	v_mov_b32_dpp v113, v59 row_ror:2 row_mask:0xf bank_mask:0xf
	v_mov_b32_dpp v80, v56 row_ror:1 row_mask:0xf bank_mask:0xf
	v_mov_b32_dpp v82, v56 row_ror:2 row_mask:0xf bank_mask:0xf
	v_mov_b32_dpp v81, v57 row_ror:1 row_mask:0xf bank_mask:0xf
	v_mov_b32_dpp v83, v57 row_ror:2 row_mask:0xf bank_mask:0xf
	s_and_b64 s[8:9], s[48:49], s[6:7]
	s_and_saveexec_b64 s[6:7], s[8:9]
	s_cbranch_execz .LBB0_311
	v_cndmask_b32_e64 v131, v130, v113, s[44:45]
	v_cndmask_b32_e64 v130, v129, v112, s[44:45]
	v_pk_fma_f32 v[130:131], v[72:73], v[130:131], v[76:77]
	v_cndmask_b32_e64 v129, v111, v128, s[42:43]
	v_cndmask_b32_e64 v128, v110, v127, s[42:43]
	v_pk_fma_f32 v[128:129], v[64:65], v[128:129], v[130:131]
	v_pk_mul_f32 v[48:49], v[48:49], v[86:87] op_sel_hi:[1,0]
	v_pk_fma_f32 v[58:59], v[58:59], v[68:69], v[128:129]
	v_pk_mul_f32 v[54:55], v[54:55], v[86:87] op_sel_hi:[1,0]
	v_mul_f32_e32 v127, 0x3d122279, v58
	v_fmaak_f32 v127, v58, v127, 0x3f4c422a
	v_mul_f32_e32 v127, v58, v127
	v_mul_f32_e32 v127, 0xc038aa3b, v127
	v_exp_f32_e32 v127, v127
	v_pk_mul_f32 v[52:53], v[52:53], v[86:87] op_sel_hi:[1,0]
	v_pk_mul_f32 v[50:51], v[50:51], v[86:87] op_sel_hi:[1,0]
	v_add_f32_e32 v127, 1.0, v127
	v_rcp_f32_e32 v128, v127
	v_mul_f32_e32 v127, 0x3d122279, v59
	v_fmaak_f32 v127, v59, v127, 0x3f4c422a
	v_mul_f32_e32 v127, v59, v127
	v_mul_f32_e32 v127, 0xc038aa3b, v127
	v_exp_f32_e32 v127, v127
	s_nop 0
	v_add_f32_e32 v127, 1.0, v127
	v_rcp_f32_e32 v129, v127
	s_nop 0
	v_pk_mul_f32 v[58:59], v[58:59], v[128:129]
	s_nop 0
	v_pk_mul_f32 v[58:59], v[48:49], v[58:59]
	v_cndmask_b32_e64 v49, v126, v109, s[44:45]
	v_cndmask_b32_e64 v48, v125, v108, s[44:45]
	v_pk_fma_f32 v[48:49], v[98:99], v[48:49], v[102:103]
	v_cndmask_b32_e64 v125, v107, v124, s[42:43]
	v_cndmask_b32_e64 v124, v106, v123, s[42:43]
	v_pk_fma_f32 v[48:49], v[90:91], v[124:125], v[48:49]
	s_nop 0
	v_pk_fma_f32 v[48:49], v[62:63], v[94:95], v[48:49]
	s_nop 0
	v_mul_f32_e32 v62, 0x3d122279, v48
	v_mul_f32_e32 v63, 0x3d122279, v49
	v_fmaak_f32 v62, v48, v62, 0x3f4c422a
	v_fmaak_f32 v63, v49, v63, 0x3f4c422a
	v_mul_f32_e32 v62, v48, v62
	v_mul_f32_e32 v63, v49, v63
	v_mul_f32_e32 v62, 0xc038aa3b, v62
	v_mul_f32_e32 v63, 0xc038aa3b, v63
	v_exp_f32_e32 v62, v62
	v_exp_f32_e32 v63, v63
	v_add_f32_e32 v62, 1.0, v62
	v_add_f32_e32 v63, 1.0, v63
	v_rcp_f32_e32 v62, v62
	v_rcp_f32_e32 v63, v63
	s_nop 0
	v_pk_mul_f32 v[48:49], v[48:49], v[62:63]
	s_nop 0
	v_pk_mul_f32 v[54:55], v[54:55], v[48:49]
	v_cndmask_b32_e64 v49, v122, v105, s[44:45]
	v_cndmask_b32_e64 v48, v120, v104, s[44:45]
	v_pk_fma_f32 v[48:49], v[96:97], v[48:49], v[100:101]
	v_cndmask_b32_e64 v63, v87, v117, s[42:43]
	v_cndmask_b32_e64 v62, v85, v115, s[42:43]
	v_pk_fma_f32 v[48:49], v[88:89], v[62:63], v[48:49]
	s_nop 0
; __device__ __forceinline__ u32x4 pack8(const f32x4& v0, const f32x4& v1) { u32x4 w; w.x = cvt_pk_bf16(v0[0], v0[1]); w.y = cvt_pk_bf16(v0[2], v0[3]); w.z = cvt_pk_bf16(v1[0], v1[1]); w.w = cvt_pk_bf16(v1[2], v1[3]); return w; }
; __device__ __forceinline__ float dpp_ror1(float v) { return __int_as_float(__builtin_amdgcn_update_dpp(0, __float_as_int(v), 0x121, 0xf, 0xf, false)); }
; __device__ __forceinline__ float dpp_ror2(float v) { return __int_as_float(__builtin_amdgcn_update_dpp(0, __float_as_int(v), 0x122, 0xf, 0xf, false)); }
;     __device__ __forceinline__ void operator()(const f32x4 (&acc)[2][2][4][2], const Unit& u, int wr, int wc, int fr, int fq) const {
;     ...
;             for (int m = 0; m < 4; ++m) { const int r = ai * HALF + wr * 64 + m * 16 + fr, tk = 254 * i - 2 + r;
;                 f32x4 o[2];
; #pragma unroll
;                 for (int n = 0; n < 2; ++n) { f32x4 cur = acc[ai][0][m][n] * rn[ai][m]; if (tk < 0) cur = (f32x4){0.f, 0.f, 0.f, 0.f};
; #pragma unroll
;                     for (int j = 0; j < 4; ++j) { const float c1 = dpp_ror1(cur[j]), c2 = dpp_ror2(cur[j]);
;                         const float p1 = fr >= 1 ? c1 : pc1[n][j], p2 = fr >= 2 ? c2 : pc2[n][j]; pc1[n][j] = c1; pc2[n][j] = c2;
;                         const float cv = bb[n][j] + w0[n][j] * p2 + w1[n][j] * p1 + w2[n][j] * cur[j];
;                         o[n][j] = gelu_t(cv) * (acc[ai][1][m][n][j] * rn[ai][m]); } }
;                 if (r >= 2 && tk < 4096) *(u32x4*)(ACT + (size_t)(b * 4096 + tk) * 2816 + f0) = pack8(o[0], o[1]); }
	v_pk_fma_f32 v[48:49], v[60:61], v[92:93], v[48:49]
	s_nop 0
	v_mul_f32_e32 v60, 0x3d122279, v48
	v_mul_f32_e32 v61, 0x3d122279, v49
	v_fmaak_f32 v60, v48, v60, 0x3f4c422a
	v_fmaak_f32 v61, v49, v61, 0x3f4c422a
	v_mul_f32_e32 v60, v48, v60
	v_mul_f32_e32 v61, v49, v61
	v_mul_f32_e32 v60, 0xc038aa3b, v60
	v_mul_f32_e32 v61, 0xc038aa3b, v61
	v_exp_f32_e32 v60, v60
	v_exp_f32_e32 v61, v61
	v_add_f32_e32 v60, 1.0, v60
	v_add_f32_e32 v61, 1.0, v61
	v_rcp_f32_e32 v60, v60
	v_rcp_f32_e32 v61, v61
	s_nop 0
	v_pk_mul_f32 v[48:49], v[48:49], v[60:61]
	s_nop 0
	v_pk_mul_f32 v[48:49], v[52:53], v[48:49]
	v_cndmask_b32_e64 v53, v121, v83, s[44:45]
	v_cndmask_b32_e64 v52, v119, v82, s[44:45]
	v_cndmask_b32_e64 v61, v81, v118, s[42:43]
	v_cndmask_b32_e64 v60, v80, v116, s[42:43]
	v_pk_fma_f32 v[52:53], v[74:75], v[52:53], v[78:79]
	v_cvt_pk_bf16_f32 v48, v48, v49
	v_pk_fma_f32 v[52:53], v[66:67], v[60:61], v[52:53]
	v_cvt_pk_bf16_f32 v49, v54, v55
	v_pk_fma_f32 v[52:53], v[56:57], v[70:71], v[52:53]
	v_add_u32_e32 v54, s71, v114
	v_mul_f32_e32 v56, 0x3d122279, v52
	v_mul_f32_e32 v57, 0x3d122279, v53
	v_fmaak_f32 v56, v52, v56, 0x3f4c422a
	v_fmaak_f32 v57, v53, v57, 0x3f4c422a
	v_mul_f32_e32 v56, v52, v56
	v_mul_f32_e32 v57, v53, v57
	v_mul_f32_e32 v56, 0xc038aa3b, v56
	v_mul_f32_e32 v57, 0xc038aa3b, v57
	v_exp_f32_e32 v56, v56
	v_exp_f32_e32 v57, v57
	v_add_f32_e32 v56, 1.0, v56
	v_add_f32_e32 v57, 1.0, v57
	v_rcp_f32_e32 v56, v56
	v_rcp_f32_e32 v57, v57
	s_nop 0
	v_pk_mul_f32 v[52:53], v[52:53], v[56:57]
	s_nop 0
	v_pk_mul_f32 v[52:53], v[50:51], v[52:53]
	v_cvt_pk_bf16_f32 v50, v58, v59
	v_cvt_pk_bf16_f32 v51, v52, v53
	v_mov_b64_e32 v[52:53], s[12:13]
	v_mad_i64_i32 v[52:53], s[8:9], v54, s34, v[52:53]
	v_lshl_add_u64 v[52:53], v[182:183], 1, v[52:53]
	global_store_dwordx4 v[52:53], v[48:51], off
.LBB0_311:
	s_or_b64 exec, exec, s[6:7]
	s_nop 0
	v_mul_f32_e32 v48, 0x4b800000, v84
	v_cndmask_b32_e64 v48, v84, v48, s[4:5]
	v_rsq_f32_e32 v48, v48
	v_add_u32_e32 v86, s77, v201
	v_mul_f32_e32 v49, 0x45800000, v48
	v_cndmask_b32_e64 v48, v48, v49, s[4:5]
	v_pk_mul_f32 v[44:45], v[44:45], v[48:49] op_sel_hi:[1,0]
	v_pk_mul_f32 v[46:47], v[46:47], v[48:49] op_sel_hi:[1,0]
	v_pk_mul_f32 v[50:51], v[40:41], v[48:49] op_sel_hi:[1,0]
	v_pk_mul_f32 v[40:41], v[42:43], v[48:49] op_sel_hi:[1,0]
	v_mov_b64_e32 v[42:43], v[50:51]
	v_cmp_gt_i32_e64 s[4:5], s83, v86
	v_mov_b32_dpp v53, v44 row_ror:1 row_mask:0xf bank_mask:0xf
	v_mov_b32_dpp v55, v44 row_ror:2 row_mask:0xf bank_mask:0xf
	v_mov_b32_dpp v54, v45 row_ror:1 row_mask:0xf bank_mask:0xf
	v_mov_b32_dpp v56, v45 row_ror:2 row_mask:0xf bank_mask:0xf
	v_mov_b32_dpp v57, v46 row_ror:1 row_mask:0xf bank_mask:0xf
	v_mov_b32_dpp v59, v46 row_ror:2 row_mask:0xf bank_mask:0xf
	v_mov_b32_dpp v58, v47 row_ror:1 row_mask:0xf bank_mask:0xf
	v_mov_b32_dpp v60, v47 row_ror:2 row_mask:0xf bank_mask:0xf
	v_mov_b32_dpp v61, v42 row_ror:1 row_mask:0xf bank_mask:0xf
	v_mov_b32_dpp v63, v42 row_ror:2 row_mask:0xf bank_mask:0xf
	v_mov_b32_dpp v62, v43 row_ror:1 row_mask:0xf bank_mask:0xf
	v_mov_b32_dpp v84, v43 row_ror:2 row_mask:0xf bank_mask:0xf
	v_mov_b32_dpp v49, v40 row_ror:1 row_mask:0xf bank_mask:0xf
	v_mov_b32_dpp v51, v40 row_ror:2 row_mask:0xf bank_mask:0xf
	v_mov_b32_dpp v50, v41 row_ror:1 row_mask:0xf bank_mask:0xf
	v_mov_b32_dpp v52, v41 row_ror:2 row_mask:0xf bank_mask:0xf
	s_and_b64 s[6:7], s[50:51], s[4:5]
	s_and_saveexec_b64 s[4:5], s[6:7]
	s_cbranch_execz .LBB0_313
	v_cndmask_b32_e64 v113, v113, v84, s[44:45]
	v_cndmask_b32_e64 v112, v112, v63, s[44:45]
	v_pk_fma_f32 v[112:113], v[72:73], v[112:113], v[76:77]
	v_cndmask_b32_e64 v111, v62, v111, s[42:43]
	v_cndmask_b32_e64 v110, v61, v110, s[42:43]
	v_pk_fma_f32 v[110:111], v[64:65], v[110:111], v[112:113]
	v_pk_mul_f32 v[32:33], v[32:33], v[48:49] op_sel_hi:[1,0]
	v_pk_fma_f32 v[42:43], v[42:43], v[68:69], v[110:111]
	v_cndmask_b32_e64 v107, v58, v107, s[42:43]
	v_mul_f32_e32 v110, 0x3d122279, v42
	v_mul_f32_e32 v111, 0x3d122279, v43
	v_fmaak_f32 v110, v42, v110, 0x3f4c422a
	v_fmaak_f32 v111, v43, v111, 0x3f4c422a
	v_mul_f32_e32 v110, v42, v110
	v_mul_f32_e32 v111, v43, v111
	v_mul_f32_e32 v110, 0xc038aa3b, v110
	v_mul_f32_e32 v111, 0xc038aa3b, v111
	v_exp_f32_e32 v110, v110
	v_exp_f32_e32 v111, v111
	v_cndmask_b32_e64 v106, v57, v106, s[42:43]
	v_pk_mul_f32 v[38:39], v[38:39], v[48:49] op_sel_hi:[1,0]
	v_add_f32_e32 v110, 1.0, v110
	v_add_f32_e32 v111, 1.0, v111
	v_rcp_f32_e32 v110, v110
	v_rcp_f32_e32 v111, v111
	v_pk_mul_f32 v[36:37], v[36:37], v[48:49] op_sel_hi:[1,0]
	v_pk_mul_f32 v[34:35], v[34:35], v[48:49] op_sel_hi:[1,0]
	v_pk_mul_f32 v[42:43], v[42:43], v[110:111]
	s_nop 0
	v_pk_mul_f32 v[42:43], v[32:33], v[42:43]
	v_cndmask_b32_e64 v33, v109, v60, s[44:45]
	v_cndmask_b32_e64 v32, v108, v59, s[44:45]
	v_pk_fma_f32 v[32:33], v[98:99], v[32:33], v[102:103]
	s_nop 0
	v_pk_fma_f32 v[32:33], v[90:91], v[106:107], v[32:33]
	s_nop 0
	v_pk_fma_f32 v[32:33], v[46:47], v[94:95], v[32:33]
	s_nop 0
	v_mul_f32_e32 v46, 0x3d122279, v32
	v_mul_f32_e32 v47, 0x3d122279, v33
	v_fmaak_f32 v46, v32, v46, 0x3f4c422a
	v_fmaak_f32 v47, v33, v47, 0x3f4c422a
	v_mul_f32_e32 v46, v32, v46
	v_mul_f32_e32 v47, v33, v47
	v_mul_f32_e32 v46, 0xc038aa3b, v46
	v_mul_f32_e32 v47, 0xc038aa3b, v47
	v_exp_f32_e32 v46, v46
	v_exp_f32_e32 v47, v47
	v_add_f32_e32 v46, 1.0, v46
	v_add_f32_e32 v47, 1.0, v47
	v_rcp_f32_e32 v46, v46
	v_rcp_f32_e32 v47, v47
	s_nop 0
	v_pk_mul_f32 v[32:33], v[32:33], v[46:47]
	s_nop 0
	v_pk_mul_f32 v[38:39], v[38:39], v[32:33]
	v_cndmask_b32_e64 v33, v105, v56, s[44:45]
	v_cndmask_b32_e64 v32, v104, v55, s[44:45]
	v_pk_fma_f32 v[32:33], v[96:97], v[32:33], v[100:101]
; __device__ __forceinline__ u32x4 pack8(const f32x4& v0, const f32x4& v1) { u32x4 w; w.x = cvt_pk_bf16(v0[0], v0[1]); w.y = cvt_pk_bf16(v0[2], v0[3]); w.z = cvt_pk_bf16(v1[0], v1[1]); w.w = cvt_pk_bf16(v1[2], v1[3]); return w; }
; __device__ __forceinline__ float dpp_ror1(float v) { return __int_as_float(__builtin_amdgcn_update_dpp(0, __float_as_int(v), 0x121, 0xf, 0xf, false)); }
; __device__ __forceinline__ float dpp_ror2(float v) { return __int_as_float(__builtin_amdgcn_update_dpp(0, __float_as_int(v), 0x122, 0xf, 0xf, false)); }
;     __device__ __forceinline__ void operator()(const f32x4 (&acc)[2][2][4][2], const Unit& u, int wr, int wc, int fr, int fq) const {
;     ...
;             for (int m = 0; m < 4; ++m) { const int r = ai * HALF + wr * 64 + m * 16 + fr, tk = 254 * i - 2 + r;
;                 f32x4 o[2];
; #pragma unroll
;                 for (int n = 0; n < 2; ++n) { f32x4 cur = acc[ai][0][m][n] * rn[ai][m]; if (tk < 0) cur = (f32x4){0.f, 0.f, 0.f, 0.f};
; #pragma unroll
;                     for (int j = 0; j < 4; ++j) { const float c1 = dpp_ror1(cur[j]), c2 = dpp_ror2(cur[j]);
;                         const float p1 = fr >= 1 ? c1 : pc1[n][j], p2 = fr >= 2 ? c2 : pc2[n][j]; pc1[n][j] = c1; pc2[n][j] = c2;
;                         const float cv = bb[n][j] + w0[n][j] * p2 + w1[n][j] * p1 + w2[n][j] * cur[j];
;                         o[n][j] = gelu_t(cv) * (acc[ai][1][m][n][j] * rn[ai][m]); } }
;                 if (r >= 2 && tk < 4096) *(u32x4*)(ACT + (size_t)(b * 4096 + tk) * 2816 + f0) = pack8(o[0], o[1]); }
	v_cndmask_b32_e64 v47, v54, v87, s[42:43]
	v_cndmask_b32_e64 v46, v53, v85, s[42:43]
	v_pk_fma_f32 v[32:33], v[88:89], v[46:47], v[32:33]
	s_nop 0
	v_pk_fma_f32 v[32:33], v[44:45], v[92:93], v[32:33]
	s_nop 0
	v_mul_f32_e32 v44, 0x3d122279, v32
	v_mul_f32_e32 v45, 0x3d122279, v33
	v_fmaak_f32 v44, v32, v44, 0x3f4c422a
	v_fmaak_f32 v45, v33, v45, 0x3f4c422a
	v_mul_f32_e32 v44, v32, v44
	v_mul_f32_e32 v45, v33, v45
	v_mul_f32_e32 v44, 0xc038aa3b, v44
	v_mul_f32_e32 v45, 0xc038aa3b, v45
	v_exp_f32_e32 v44, v44
	v_exp_f32_e32 v45, v45
	v_add_f32_e32 v44, 1.0, v44
	v_add_f32_e32 v45, 1.0, v45
	v_rcp_f32_e32 v44, v44
	v_rcp_f32_e32 v45, v45
	s_nop 0
	v_pk_mul_f32 v[32:33], v[32:33], v[44:45]
	s_nop 0
	v_pk_mul_f32 v[32:33], v[36:37], v[32:33]
	v_cndmask_b32_e64 v37, v83, v52, s[44:45]
	v_cndmask_b32_e64 v36, v82, v51, s[44:45]
	v_cndmask_b32_e64 v45, v50, v81, s[42:43]
	v_cndmask_b32_e64 v44, v49, v80, s[42:43]
	v_pk_fma_f32 v[36:37], v[74:75], v[36:37], v[78:79]
	v_cvt_pk_bf16_f32 v32, v32, v33
	v_pk_fma_f32 v[36:37], v[66:67], v[44:45], v[36:37]
	v_cvt_pk_bf16_f32 v33, v38, v39
	v_pk_fma_f32 v[36:37], v[40:41], v[70:71], v[36:37]
	v_add_u32_e32 v38, s71, v86
	v_mul_f32_e32 v40, 0x3d122279, v36
	v_mul_f32_e32 v41, 0x3d122279, v37
	v_fmaak_f32 v40, v36, v40, 0x3f4c422a
	v_fmaak_f32 v41, v37, v41, 0x3f4c422a
	v_mul_f32_e32 v40, v36, v40
	v_mul_f32_e32 v41, v37, v41
	v_mul_f32_e32 v40, 0xc038aa3b, v40
	v_mul_f32_e32 v41, 0xc038aa3b, v41
	v_exp_f32_e32 v40, v40
	v_exp_f32_e32 v41, v41
	v_add_f32_e32 v40, 1.0, v40
	v_add_f32_e32 v41, 1.0, v41
	v_rcp_f32_e32 v40, v40
	v_rcp_f32_e32 v41, v41
	s_nop 0
	v_pk_mul_f32 v[36:37], v[36:37], v[40:41]
	s_nop 0
	v_pk_mul_f32 v[36:37], v[34:35], v[36:37]
	v_cvt_pk_bf16_f32 v34, v42, v43
	v_cvt_pk_bf16_f32 v35, v36, v37
	v_mov_b64_e32 v[36:37], s[12:13]
	v_mad_i64_i32 v[36:37], s[6:7], v38, s34, v[36:37]
	v_lshl_add_u64 v[36:37], v[182:183], 1, v[36:37]
	global_store_dwordx4 v[36:37], v[32:35], off
.LBB0_313:
	s_or_b64 exec, exec, s[4:5]
	s_nop 0
	v_mul_f32_e32 v32, 0x4b800000, v185
	v_cndmask_b32_e32 v32, v185, v32, vcc
	v_rsq_f32_e32 v32, v32
	v_add_u32_e32 v80, s77, v202
	v_mul_f32_e32 v33, 0x45800000, v32
	v_cndmask_b32_e32 v32, v32, v33, vcc
	v_pk_mul_f32 v[28:29], v[28:29], v[32:33] op_sel_hi:[1,0]
	v_pk_mul_f32 v[30:31], v[30:31], v[32:33] op_sel_hi:[1,0]
	v_pk_mul_f32 v[34:35], v[24:25], v[32:33] op_sel_hi:[1,0]
	v_pk_mul_f32 v[24:25], v[26:27], v[32:33] op_sel_hi:[1,0]
	v_mov_b64_e32 v[26:27], v[34:35]
	v_cmp_gt_i32_e32 vcc, s83, v80
	v_mov_b32_dpp v45, v28 row_ror:1 row_mask:0xf bank_mask:0xf
	v_mov_b32_dpp v47, v28 row_ror:2 row_mask:0xf bank_mask:0xf
	v_mov_b32_dpp v46, v29 row_ror:1 row_mask:0xf bank_mask:0xf
	v_mov_b32_dpp v48, v29 row_ror:2 row_mask:0xf bank_mask:0xf
	v_mov_b32_dpp v41, v30 row_ror:1 row_mask:0xf bank_mask:0xf
	v_mov_b32_dpp v43, v30 row_ror:2 row_mask:0xf bank_mask:0xf
	v_mov_b32_dpp v42, v31 row_ror:1 row_mask:0xf bank_mask:0xf
	v_mov_b32_dpp v44, v31 row_ror:2 row_mask:0xf bank_mask:0xf
	v_mov_b32_dpp v37, v26 row_ror:1 row_mask:0xf bank_mask:0xf
	v_mov_b32_dpp v39, v26 row_ror:2 row_mask:0xf bank_mask:0xf
	v_mov_b32_dpp v38, v27 row_ror:1 row_mask:0xf bank_mask:0xf
	v_mov_b32_dpp v40, v27 row_ror:2 row_mask:0xf bank_mask:0xf
	v_mov_b32_dpp v33, v24 row_ror:1 row_mask:0xf bank_mask:0xf
	v_mov_b32_dpp v35, v24 row_ror:2 row_mask:0xf bank_mask:0xf
	v_mov_b32_dpp v34, v25 row_ror:1 row_mask:0xf bank_mask:0xf
	v_mov_b32_dpp v36, v25 row_ror:2 row_mask:0xf bank_mask:0xf
	s_and_b64 s[6:7], s[52:53], vcc
	s_and_saveexec_b64 s[4:5], s[6:7]
	s_cbranch_execz .LBB0_315
	v_cndmask_b32_e64 v83, v84, v40, s[44:45]
	v_cndmask_b32_e64 v82, v63, v39, s[44:45]
	v_pk_fma_f32 v[82:83], v[72:73], v[82:83], v[76:77]
	v_cndmask_b32_e64 v63, v38, v62, s[42:43]
	v_cndmask_b32_e64 v62, v37, v61, s[42:43]
	v_pk_fma_f32 v[62:63], v[64:65], v[62:63], v[82:83]
	v_pk_mul_f32 v[16:17], v[16:17], v[32:33] op_sel_hi:[1,0]
	v_pk_fma_f32 v[26:27], v[26:27], v[68:69], v[62:63]
	v_pk_mul_f32 v[22:23], v[22:23], v[32:33] op_sel_hi:[1,0]
	v_mul_f32_e32 v61, 0x3d122279, v26
	v_fmaak_f32 v61, v26, v61, 0x3f4c422a
	v_mul_f32_e32 v61, v26, v61
	v_mul_f32_e32 v61, 0xc038aa3b, v61
	v_exp_f32_e32 v61, v61
	v_pk_mul_f32 v[20:21], v[20:21], v[32:33] op_sel_hi:[1,0]
	v_pk_mul_f32 v[18:19], v[18:19], v[32:33] op_sel_hi:[1,0]
	v_add_f32_e32 v61, 1.0, v61
	v_rcp_f32_e32 v62, v61
	v_mul_f32_e32 v61, 0x3d122279, v27
	v_fmaak_f32 v61, v27, v61, 0x3f4c422a
	v_mul_f32_e32 v61, v27, v61
	v_mul_f32_e32 v61, 0xc038aa3b, v61
	v_exp_f32_e32 v61, v61
	s_nop 0
	v_add_f32_e32 v61, 1.0, v61
	v_rcp_f32_e32 v63, v61
	s_nop 0
	v_pk_mul_f32 v[26:27], v[26:27], v[62:63]
	s_nop 0
	v_pk_mul_f32 v[26:27], v[16:17], v[26:27]
	v_cndmask_b32_e64 v17, v60, v44, s[44:45]
	v_cndmask_b32_e64 v16, v59, v43, s[44:45]
	v_pk_fma_f32 v[16:17], v[98:99], v[16:17], v[102:103]
	v_cndmask_b32_e64 v59, v42, v58, s[42:43]
	v_cndmask_b32_e64 v58, v41, v57, s[42:43]
	v_pk_fma_f32 v[16:17], v[90:91], v[58:59], v[16:17]
	s_nop 0
	v_pk_fma_f32 v[16:17], v[30:31], v[94:95], v[16:17]
	s_nop 0
	v_mul_f32_e32 v30, 0x3d122279, v16
	v_mul_f32_e32 v31, 0x3d122279, v17
	v_fmaak_f32 v30, v16, v30, 0x3f4c422a
	v_fmaak_f32 v31, v17, v31, 0x3f4c422a
	v_mul_f32_e32 v30, v16, v30
	v_mul_f32_e32 v31, v17, v31
	v_mul_f32_e32 v30, 0xc038aa3b, v30
	v_mul_f32_e32 v31, 0xc038aa3b, v31
	v_exp_f32_e32 v30, v30
	v_exp_f32_e32 v31, v31
	v_add_f32_e32 v30, 1.0, v30
	v_add_f32_e32 v31, 1.0, v31
	v_rcp_f32_e32 v30, v30
	v_rcp_f32_e32 v31, v31
	s_nop 0
	v_pk_mul_f32 v[16:17], v[16:17], v[30:31]
	s_nop 0
	v_pk_mul_f32 v[22:23], v[22:23], v[16:17]
	v_cndmask_b32_e64 v17, v56, v48, s[44:45]
; __device__ __forceinline__ u32x4 pack8(const f32x4& v0, const f32x4& v1) { u32x4 w; w.x = cvt_pk_bf16(v0[0], v0[1]); w.y = cvt_pk_bf16(v0[2], v0[3]); w.z = cvt_pk_bf16(v1[0], v1[1]); w.w = cvt_pk_bf16(v1[2], v1[3]); return w; }
; __device__ __forceinline__ float dpp_ror1(float v) { return __int_as_float(__builtin_amdgcn_update_dpp(0, __float_as_int(v), 0x121, 0xf, 0xf, false)); }
; __device__ __forceinline__ float dpp_ror2(float v) { return __int_as_float(__builtin_amdgcn_update_dpp(0, __float_as_int(v), 0x122, 0xf, 0xf, false)); }
;     __device__ __forceinline__ void operator()(const f32x4 (&acc)[2][2][4][2], const Unit& u, int wr, int wc, int fr, int fq) const {
;     ...
;                     for (int j = 0; j < 4; ++j) { const float c1 = dpp_ror1(cur[j]), c2 = dpp_ror2(cur[j]);
;                         const float p1 = fr >= 1 ? c1 : pc1[n][j], p2 = fr >= 2 ? c2 : pc2[n][j]; pc1[n][j] = c1; pc2[n][j] = c2;
;                         const float cv = bb[n][j] + w0[n][j] * p2 + w1[n][j] * p1 + w2[n][j] * cur[j];
;                         o[n][j] = gelu_t(cv) * (acc[ai][1][m][n][j] * rn[ai][m]); } }
;                 if (r >= 2 && tk < 4096) *(u32x4*)(ACT + (size_t)(b * 4096 + tk) * 2816 + f0) = pack8(o[0], o[1]); }
	v_cndmask_b32_e64 v16, v55, v47, s[44:45]
	v_pk_fma_f32 v[16:17], v[96:97], v[16:17], v[100:101]
	v_cndmask_b32_e64 v31, v46, v54, s[42:43]
	v_cndmask_b32_e64 v30, v45, v53, s[42:43]
	v_pk_fma_f32 v[16:17], v[88:89], v[30:31], v[16:17]
	s_nop 0
	v_pk_fma_f32 v[16:17], v[28:29], v[92:93], v[16:17]
	s_nop 0
	v_mul_f32_e32 v28, 0x3d122279, v16
	v_mul_f32_e32 v29, 0x3d122279, v17
	v_fmaak_f32 v28, v16, v28, 0x3f4c422a
	v_fmaak_f32 v29, v17, v29, 0x3f4c422a
	v_mul_f32_e32 v28, v16, v28
	v_mul_f32_e32 v29, v17, v29
	v_mul_f32_e32 v28, 0xc038aa3b, v28
	v_mul_f32_e32 v29, 0xc038aa3b, v29
	v_exp_f32_e32 v28, v28
	v_exp_f32_e32 v29, v29
	v_add_f32_e32 v28, 1.0, v28
	v_add_f32_e32 v29, 1.0, v29
	v_rcp_f32_e32 v28, v28
	v_rcp_f32_e32 v29, v29
	s_nop 0
	v_pk_mul_f32 v[16:17], v[16:17], v[28:29]
	s_nop 0
	v_pk_mul_f32 v[16:17], v[20:21], v[16:17]
	v_cndmask_b32_e64 v21, v52, v36, s[44:45]
	v_cndmask_b32_e64 v20, v51, v35, s[44:45]
	v_cndmask_b32_e64 v29, v34, v50, s[42:43]
	v_cndmask_b32_e64 v28, v33, v49, s[42:43]
	v_pk_fma_f32 v[20:21], v[74:75], v[20:21], v[78:79]
	v_cvt_pk_bf16_f32 v16, v16, v17
	v_pk_fma_f32 v[20:21], v[66:67], v[28:29], v[20:21]
	v_cvt_pk_bf16_f32 v17, v22, v23
	v_pk_fma_f32 v[20:21], v[24:25], v[70:71], v[20:21]
	v_add_u32_e32 v22, s71, v80
	v_mul_f32_e32 v24, 0x3d122279, v20
	v_mul_f32_e32 v25, 0x3d122279, v21
	v_fmaak_f32 v24, v20, v24, 0x3f4c422a
	v_fmaak_f32 v25, v21, v25, 0x3f4c422a
	v_mul_f32_e32 v24, v20, v24
	v_mul_f32_e32 v25, v21, v25
	v_mul_f32_e32 v24, 0xc038aa3b, v24
	v_mul_f32_e32 v25, 0xc038aa3b, v25
	v_exp_f32_e32 v24, v24
	v_exp_f32_e32 v25, v25
	v_add_f32_e32 v24, 1.0, v24
	v_add_f32_e32 v25, 1.0, v25
	v_rcp_f32_e32 v24, v24
	v_rcp_f32_e32 v25, v25
	s_nop 0
	v_pk_mul_f32 v[20:21], v[20:21], v[24:25]
	s_nop 0
	v_pk_mul_f32 v[20:21], v[18:19], v[20:21]
	v_cvt_pk_bf16_f32 v18, v26, v27
	v_cvt_pk_bf16_f32 v19, v20, v21
	v_mov_b64_e32 v[20:21], s[12:13]
	v_mad_i64_i32 v[20:21], s[6:7], v22, s34, v[20:21]
	v_lshl_add_u64 v[20:21], v[182:183], 1, v[20:21]
	global_store_dwordx4 v[20:21], v[16:19], off
; __device__ __forceinline__ u32x4 pack8(const f32x4& v0, const f32x4& v1) { u32x4 w; w.x = cvt_pk_bf16(v0[0], v0[1]); w.y = cvt_pk_bf16(v0[2], v0[3]); w.z = cvt_pk_bf16(v1[0], v1[1]); w.w = cvt_pk_bf16(v1[2], v1[3]); return w; }
; __device__ __forceinline__ float dpp_ror1(float v) { return __int_as_float(__builtin_amdgcn_update_dpp(0, __float_as_int(v), 0x121, 0xf, 0xf, false)); }
; __device__ __forceinline__ float dpp_ror2(float v) { return __int_as_float(__builtin_amdgcn_update_dpp(0, __float_as_int(v), 0x122, 0xf, 0xf, false)); }
;     __device__ __forceinline__ void operator()(const f32x4 (&acc)[2][2][4][2], const Unit& u, int wr, int wc, int fr, int fq) const {
;     ...
;             for (int m = 0; m < 4; ++m) { const int r = ai * HALF + wr * 64 + m * 16 + fr, tk = 254 * i - 2 + r;
;                 f32x4 o[2];
; #pragma unroll
;                 for (int n = 0; n < 2; ++n) { f32x4 cur = acc[ai][0][m][n] * rn[ai][m]; if (tk < 0) cur = (f32x4){0.f, 0.f, 0.f, 0.f};
; #pragma unroll
;                     for (int j = 0; j < 4; ++j) { const float c1 = dpp_ror1(cur[j]), c2 = dpp_ror2(cur[j]);
;                         const float p1 = fr >= 1 ? c1 : pc1[n][j], p2 = fr >= 2 ? c2 : pc2[n][j]; pc1[n][j] = c1; pc2[n][j] = c2;
;                         const float cv = bb[n][j] + w0[n][j] * p2 + w1[n][j] * p1 + w2[n][j] * cur[j];
;                         o[n][j] = gelu_t(cv) * (acc[ai][1][m][n][j] * rn[ai][m]); } }
;                 if (r >= 2 && tk < 4096) *(u32x4*)(ACT + (size_t)(b * 4096 + tk) * 2816 + f0) = pack8(o[0], o[1]); }
.LBB0_315:
	s_or_b64 exec, exec, s[4:5]
	s_nop 0
	v_add_u32_e32 v16, s77, v203
	v_pk_mul_f32 v[18:19], v[14:15], v[184:185] op_sel_hi:[1,0]
	v_pk_mul_f32 v[12:13], v[12:13], v[184:185] op_sel_hi:[1,0]
	v_pk_mul_f32 v[8:9], v[8:9], v[184:185] op_sel_hi:[1,0]
	s_nop 0
	v_mov_b64_e32 v[14:15], v[12:13]
	v_mov_b64_e32 v[12:13], v[18:19]
	v_pk_mul_f32 v[18:19], v[10:11], v[184:185] op_sel_hi:[1,0]
	v_mov_b64_e32 v[10:11], v[8:9]
	v_mov_b64_e32 v[8:9], v[18:19]
	v_cmp_gt_i32_e32 vcc, s83, v16
	v_mov_b32_dpp v29, v14 row_ror:1 row_mask:0xf bank_mask:0xf
	v_mov_b32_dpp v31, v14 row_ror:2 row_mask:0xf bank_mask:0xf
	v_mov_b32_dpp v30, v15 row_ror:1 row_mask:0xf bank_mask:0xf
	v_mov_b32_dpp v32, v15 row_ror:2 row_mask:0xf bank_mask:0xf
	v_mov_b32_dpp v25, v12 row_ror:1 row_mask:0xf bank_mask:0xf
	v_mov_b32_dpp v27, v12 row_ror:2 row_mask:0xf bank_mask:0xf
	v_mov_b32_dpp v26, v13 row_ror:1 row_mask:0xf bank_mask:0xf
	v_mov_b32_dpp v28, v13 row_ror:2 row_mask:0xf bank_mask:0xf
	v_mov_b32_dpp v21, v10 row_ror:1 row_mask:0xf bank_mask:0xf
	v_mov_b32_dpp v23, v10 row_ror:2 row_mask:0xf bank_mask:0xf
	v_mov_b32_dpp v22, v11 row_ror:1 row_mask:0xf bank_mask:0xf
	v_mov_b32_dpp v24, v11 row_ror:2 row_mask:0xf bank_mask:0xf
	v_mov_b32_dpp v17, v8 row_ror:1 row_mask:0xf bank_mask:0xf
	v_mov_b32_dpp v19, v8 row_ror:2 row_mask:0xf bank_mask:0xf
	v_mov_b32_dpp v18, v9 row_ror:1 row_mask:0xf bank_mask:0xf
	v_mov_b32_dpp v20, v9 row_ror:2 row_mask:0xf bank_mask:0xf
	s_and_b64 s[6:7], s[54:55], vcc
	s_and_saveexec_b64 s[4:5], s[6:7]
	s_cbranch_execz .LBB0_317
	v_cndmask_b32_e64 v49, v48, v32, s[44:45]
	v_cndmask_b32_e64 v48, v47, v31, s[44:45]
	v_pk_fma_f32 v[48:49], v[96:97], v[48:49], v[100:101]
	v_cndmask_b32_e64 v31, v30, v46, s[42:43]
	v_cndmask_b32_e64 v30, v29, v45, s[42:43]
	v_pk_fma_f32 v[30:31], v[88:89], v[30:31], v[48:49]
	v_pk_mul_f32 v[4:5], v[4:5], v[184:185] op_sel_hi:[1,0]
	v_pk_fma_f32 v[14:15], v[14:15], v[92:93], v[30:31]
	v_pk_mul_f32 v[6:7], v[6:7], v[184:185] op_sel_hi:[1,0]
	v_mul_f32_e32 v29, 0x3d122279, v14
	v_fmaak_f32 v29, v14, v29, 0x3f4c422a
	v_mul_f32_e32 v29, v14, v29
	v_mul_f32_e32 v29, 0xc038aa3b, v29
	v_exp_f32_e32 v29, v29
	v_pk_mul_f32 v[0:1], v[0:1], v[184:185] op_sel_hi:[1,0]
	v_pk_mul_f32 v[2:3], v[2:3], v[184:185] op_sel_hi:[1,0]
	v_add_f32_e32 v29, 1.0, v29
	v_rcp_f32_e32 v30, v29
	v_mul_f32_e32 v29, 0x3d122279, v15
	v_fmaak_f32 v29, v15, v29, 0x3f4c422a
	v_mul_f32_e32 v29, v15, v29
	v_mul_f32_e32 v29, 0xc038aa3b, v29
	v_exp_f32_e32 v29, v29
	s_nop 0
	v_add_f32_e32 v29, 1.0, v29
	v_rcp_f32_e32 v31, v29
	s_nop 0
	v_pk_mul_f32 v[14:15], v[14:15], v[30:31]
	s_nop 0
	v_pk_mul_f32 v[4:5], v[4:5], v[14:15]
	v_cndmask_b32_e64 v15, v44, v28, s[44:45]
	v_cndmask_b32_e64 v14, v43, v27, s[44:45]
	v_pk_fma_f32 v[14:15], v[98:99], v[14:15], v[102:103]
	v_cndmask_b32_e64 v27, v26, v42, s[42:43]
	v_cndmask_b32_e64 v26, v25, v41, s[42:43]
	v_pk_fma_f32 v[14:15], v[90:91], v[26:27], v[14:15]
	s_nop 0
	v_pk_fma_f32 v[12:13], v[12:13], v[94:95], v[14:15]
	s_nop 0
	v_mul_f32_e32 v14, 0x3d122279, v12
	v_mul_f32_e32 v15, 0x3d122279, v13
	v_fmaak_f32 v14, v12, v14, 0x3f4c422a
	v_fmaak_f32 v15, v13, v15, 0x3f4c422a
	v_mul_f32_e32 v14, v12, v14
	v_mul_f32_e32 v15, v13, v15
	v_mul_f32_e32 v14, 0xc038aa3b, v14
	v_mul_f32_e32 v15, 0xc038aa3b, v15
	v_exp_f32_e32 v14, v14
	v_exp_f32_e32 v15, v15
	v_add_f32_e32 v14, 1.0, v14
	v_add_f32_e32 v15, 1.0, v15
	v_rcp_f32_e32 v14, v14
	v_rcp_f32_e32 v15, v15
	s_nop 0
	v_pk_mul_f32 v[12:13], v[12:13], v[14:15]
	s_nop 0
	v_pk_mul_f32 v[6:7], v[6:7], v[12:13]
	v_cndmask_b32_e64 v13, v40, v24, s[44:45]
	v_cndmask_b32_e64 v12, v39, v23, s[44:45]
	v_pk_fma_f32 v[12:13], v[72:73], v[12:13], v[76:77]
	v_cndmask_b32_e64 v15, v22, v38, s[42:43]
	v_cndmask_b32_e64 v14, v21, v37, s[42:43]
	v_pk_fma_f32 v[12:13], v[64:65], v[14:15], v[12:13]
	s_nop 0
	v_pk_fma_f32 v[10:11], v[10:11], v[68:69], v[12:13]
	s_nop 0
	v_mul_f32_e32 v12, 0x3d122279, v10
	v_mul_f32_e32 v13, 0x3d122279, v11
	v_fmaak_f32 v12, v10, v12, 0x3f4c422a
	v_fmaak_f32 v13, v11, v13, 0x3f4c422a
	v_mul_f32_e32 v12, v10, v12
	v_mul_f32_e32 v13, v11, v13
	v_mul_f32_e32 v12, 0xc038aa3b, v12
	v_mul_f32_e32 v13, 0xc038aa3b, v13
	v_exp_f32_e32 v12, v12
	v_exp_f32_e32 v13, v13
	v_add_f32_e32 v12, 1.0, v12
	v_add_f32_e32 v13, 1.0, v13
	v_rcp_f32_e32 v12, v12
	v_rcp_f32_e32 v13, v13
	s_nop 0
	v_pk_mul_f32 v[10:11], v[10:11], v[12:13]
	s_nop 0
	v_pk_mul_f32 v[10:11], v[0:1], v[10:11]
	v_cndmask_b32_e64 v1, v36, v20, s[44:45]
	v_cndmask_b32_e64 v0, v35, v19, s[44:45]
	v_cndmask_b32_e64 v13, v18, v34, s[42:43]
	v_cndmask_b32_e64 v12, v17, v33, s[42:43]
	v_pk_fma_f32 v[0:1], v[74:75], v[0:1], v[78:79]
	s_nop 0
	v_pk_fma_f32 v[0:1], v[66:67], v[12:13], v[0:1]
	s_nop 0
	v_pk_fma_f32 v[0:1], v[8:9], v[70:71], v[0:1]
	s_nop 0
	v_mul_f32_e32 v8, 0x3d122279, v0
	v_mul_f32_e32 v9, 0x3d122279, v1
	v_fmaak_f32 v8, v0, v8, 0x3f4c422a
	v_fmaak_f32 v9, v1, v9, 0x3f4c422a
	v_mul_f32_e32 v8, v0, v8
	v_mul_f32_e32 v9, v1, v9
	v_mul_f32_e32 v8, 0xc038aa3b, v8
	v_mul_f32_e32 v9, 0xc038aa3b, v9
	v_exp_f32_e32 v8, v8
	v_exp_f32_e32 v9, v9
	v_add_f32_e32 v8, 1.0, v8
	v_add_f32_e32 v9, 1.0, v9
	v_rcp_f32_e32 v8, v8
	v_rcp_f32_e32 v9, v9
	s_nop 0
	v_pk_mul_f32 v[0:1], v[0:1], v[8:9]
	s_nop 0
	v_pk_mul_f32 v[8:9], v[2:3], v[0:1]
	v_cvt_pk_bf16_f32 v0, v4, v5
	v_cvt_pk_bf16_f32 v1, v6, v7
	v_add_u32_e32 v6, s71, v16
	v_mov_b64_e32 v[4:5], s[12:13]
	v_mad_i64_i32 v[4:5], s[6:7], v6, s34, v[4:5]
	v_cvt_pk_bf16_f32 v2, v10, v11
	v_cvt_pk_bf16_f32 v3, v8, v9
	v_lshl_add_u64 v[4:5], v[182:183], 1, v[4:5]
	global_store_dwordx4 v[4:5], v[0:3], off
